# attention P7: QK^T MFMA section hand-scheduled with 5-deep LDS read-ahead; K and V^T staging issue all 16 loads at once, V^T partly fetched before the softmax
# speedup vs baseline: 1.0051x; 1.0051x over previous
.LBB0_501:
	s_lshl_b32 s0, s9, 2
	s_and_b32 s6, s0, 0xffffff00
	s_lshl_b32 s0, s9, 8
	s_and_b32 s7, s0, 0x300
	v_or_b32_e32 v252, s6, v187
	v_lshlrev_b32_e32 v252, 11, v252
	s_lshl_b32 s0, s7, 1
	v_add3_u32 v252, v252, v190, s0
	s_mov_b64 s[14:15], s[64:65]
	v_add_u32_e32 v253, 0x10800, v196
	global_load_dwordx4 v[4:7], v252, s[14:15]
	s_add_u32 s14, s14, 0x8000
	s_addc_u32 s15, s15, 0
	global_load_dwordx4 v[8:11], v252, s[14:15]
	s_add_u32 s14, s14, 0x8000
	s_addc_u32 s15, s15, 0
	global_load_dwordx4 v[12:15], v252, s[14:15]
	s_add_u32 s14, s14, 0x8000
	s_addc_u32 s15, s15, 0
	global_load_dwordx4 v[16:19], v252, s[14:15]
	s_add_u32 s14, s14, 0x8000
	s_addc_u32 s15, s15, 0
	global_load_dwordx4 v[20:23], v252, s[14:15]
	s_add_u32 s14, s14, 0x8000
	s_addc_u32 s15, s15, 0
	global_load_dwordx4 v[24:27], v252, s[14:15]
	s_add_u32 s14, s14, 0x8000
	s_addc_u32 s15, s15, 0
	global_load_dwordx4 v[28:31], v252, s[14:15]
	s_add_u32 s14, s14, 0x8000
	s_addc_u32 s15, s15, 0
	global_load_dwordx4 v[32:35], v252, s[14:15]
	s_add_u32 s14, s14, 0x8000
	s_addc_u32 s15, s15, 0
	global_load_dwordx4 v[36:39], v252, s[14:15]
	s_add_u32 s14, s14, 0x8000
	s_addc_u32 s15, s15, 0
	global_load_dwordx4 v[40:43], v252, s[14:15]
	s_add_u32 s14, s14, 0x8000
	s_addc_u32 s15, s15, 0
	global_load_dwordx4 v[44:47], v252, s[14:15]
	s_add_u32 s14, s14, 0x8000
	s_addc_u32 s15, s15, 0
	global_load_dwordx4 v[48:51], v252, s[14:15]
	s_add_u32 s14, s14, 0x8000
	s_addc_u32 s15, s15, 0
	global_load_dwordx4 v[52:55], v252, s[14:15]
	s_add_u32 s14, s14, 0x8000
	s_addc_u32 s15, s15, 0
	global_load_dwordx4 v[56:59], v252, s[14:15]
	s_add_u32 s14, s14, 0x8000
	s_addc_u32 s15, s15, 0
	global_load_dwordx4 v[128:131], v252, s[14:15]
	s_add_u32 s14, s14, 0x8000
	s_addc_u32 s15, s15, 0
	global_load_dwordx4 v[132:135], v252, s[14:15]
	s_add_u32 s14, s14, 0x8000
	s_addc_u32 s15, s15, 0
	s_lshl_b32 s0, s9, 6
	s_and_b32 s0, s0, 0xffffff00
	v_add_u32_e32 v0, s0, v197
	v_ashrrev_i32_e32 v1, 31, v0
	v_lshlrev_b64 v[194:195], 10, v[0:1]
	v_lshlrev_b64 v[0:1], 11, v[0:1]
	v_lshl_add_u64 v[0:1], s[58:59], 0, v[0:1]
	s_lshl_b32 s0, s7, 1
	v_lshl_add_u64 v[0:1], v[0:1], 0, s[0:1]
	v_lshl_add_u64 v[0:1], v[0:1], 0, v[192:193]
	global_load_dwordx4 v[112:115], v[0:1], off
	v_add_co_u32_e32 v2, vcc, 0x8000, v0
	v_readlane_b32 s12, v254, 37
	s_nop 0
	v_addc_co_u32_e32 v3, vcc, 0, v1, vcc
	global_load_dwordx4 v[124:127], v[2:3], off
	global_load_dwordx4 v[116:119], v[0:1], off offset:64
	global_load_dwordx4 v[120:123], v[2:3], off offset:64
	global_load_dwordx4 v[104:107], v[0:1], off offset:128
	global_load_dwordx4 v[108:111], v[2:3], off offset:128
	global_load_dwordx4 v[96:99], v[0:1], off offset:192
	global_load_dwordx4 v[100:103], v[2:3], off offset:192
	global_load_dwordx4 v[88:91], v[0:1], off offset:256
	global_load_dwordx4 v[92:95], v[2:3], off offset:256
	global_load_dwordx4 v[80:83], v[0:1], off offset:320
	global_load_dwordx4 v[84:87], v[2:3], off offset:320
	global_load_dwordx4 v[68:71], v[0:1], off offset:384
	global_load_dwordx4 v[72:75], v[2:3], off offset:384
	global_load_dwordx4 v[60:63], v[0:1], off offset:448
	global_load_dwordx4 v[76:79], v[2:3], off offset:448
	s_waitcnt vmcnt(31)
	ds_write_b128 v196, v[4:7]
	s_waitcnt vmcnt(30)
	ds_write_b128 v196, v[8:11] offset:8448
	s_waitcnt vmcnt(29)
	ds_write_b128 v196, v[12:15] offset:16896
	s_waitcnt vmcnt(28)
	ds_write_b128 v196, v[16:19] offset:25344
	s_waitcnt vmcnt(27)
	ds_write_b128 v196, v[20:23] offset:33792
	s_waitcnt vmcnt(26)
	ds_write_b128 v196, v[24:27] offset:42240
	s_waitcnt vmcnt(25)
	ds_write_b128 v196, v[28:31] offset:50688
	s_waitcnt vmcnt(24)
	ds_write_b128 v196, v[32:35] offset:59136
	s_waitcnt vmcnt(23)
	ds_write_b128 v253, v[36:39]
	s_waitcnt vmcnt(22)
	ds_write_b128 v253, v[40:43] offset:8448
	s_waitcnt vmcnt(21)
	ds_write_b128 v253, v[44:47] offset:16896
	s_waitcnt vmcnt(20)
	ds_write_b128 v253, v[48:51] offset:25344
	s_waitcnt vmcnt(19)
	ds_write_b128 v253, v[52:55] offset:33792
	s_waitcnt vmcnt(18)
	ds_write_b128 v253, v[56:59] offset:42240
	s_waitcnt vmcnt(17)
	ds_write_b128 v253, v[128:131] offset:50688
	s_waitcnt vmcnt(16)
	ds_write_b128 v253, v[132:135] offset:59136
	s_waitcnt lgkmcnt(0)
	s_barrier
	v_readlane_b32 s13, v254, 38
	s_mov_b32 s10, 0
	ds_read_b128 v[228:231], v212
	ds_read_b128 v[232:235], v212 offset:64
	ds_read_b128 v[236:239], v212 offset:128
	ds_read_b128 v[240:243], v212 offset:192
	ds_read_b128 v[244:247], v212 offset:256
	s_waitcnt vmcnt(0)
	s_waitcnt lgkmcnt(4)
	v_mfma_f32_16x16x32_bf16 v[64:67], v[228:231], v[112:115], 0
	v_mfma_f32_16x16x32_bf16 v[0:3], v[228:231], v[124:127], 0
	ds_read_b128 v[228:231], v212 offset:320
	s_waitcnt lgkmcnt(4)
	v_mfma_f32_16x16x32_bf16 v[64:67], v[232:235], v[116:119], v[64:67]
	v_mfma_f32_16x16x32_bf16 v[0:3], v[232:235], v[120:123], v[0:3]
	ds_read_b128 v[232:235], v212 offset:384
	s_waitcnt lgkmcnt(4)
	v_mfma_f32_16x16x32_bf16 v[64:67], v[236:239], v[104:107], v[64:67]
	v_mfma_f32_16x16x32_bf16 v[0:3], v[236:239], v[108:111], v[0:3]
	ds_read_b128 v[236:239], v212 offset:448
	s_waitcnt lgkmcnt(4)
	v_mfma_f32_16x16x32_bf16 v[64:67], v[240:243], v[96:99], v[64:67]
	v_mfma_f32_16x16x32_bf16 v[0:3], v[240:243], v[100:103], v[0:3]
	ds_read_b128 v[240:243], v212 offset:8448
	s_waitcnt lgkmcnt(4)
	v_mfma_f32_16x16x32_bf16 v[64:67], v[244:247], v[88:91], v[64:67]
	v_mfma_f32_16x16x32_bf16 v[0:3], v[244:247], v[92:95], v[0:3]
	ds_read_b128 v[244:247], v212 offset:8512
	s_waitcnt lgkmcnt(4)
	v_mfma_f32_16x16x32_bf16 v[64:67], v[228:231], v[80:83], v[64:67]
	v_mfma_f32_16x16x32_bf16 v[0:3], v[228:231], v[84:87], v[0:3]
	ds_read_b128 v[228:231], v212 offset:8576
	s_waitcnt lgkmcnt(4)
	v_mfma_f32_16x16x32_bf16 v[64:67], v[232:235], v[68:71], v[64:67]
	v_mfma_f32_16x16x32_bf16 v[0:3], v[232:235], v[72:75], v[0:3]
	ds_read_b128 v[232:235], v212 offset:8640
	s_waitcnt lgkmcnt(4)
	v_mfma_f32_16x16x32_bf16 v[64:67], v[236:239], v[60:63], v[64:67]
	v_mfma_f32_16x16x32_bf16 v[0:3], v[236:239], v[76:79], v[0:3]
	ds_read_b128 v[236:239], v212 offset:8704
	s_waitcnt lgkmcnt(4)
	v_mfma_f32_16x16x32_bf16 v[128:131], v[240:243], v[112:115], 0
	v_mfma_f32_16x16x32_bf16 v[4:7], v[240:243], v[124:127], 0
	ds_read_b128 v[240:243], v212 offset:8768
	s_waitcnt lgkmcnt(4)
	v_mfma_f32_16x16x32_bf16 v[128:131], v[244:247], v[116:119], v[128:131]
	v_mfma_f32_16x16x32_bf16 v[4:7], v[244:247], v[120:123], v[4:7]
	ds_read_b128 v[244:247], v212 offset:8832
	s_waitcnt lgkmcnt(4)
	v_mfma_f32_16x16x32_bf16 v[128:131], v[228:231], v[104:107], v[128:131]
	v_mfma_f32_16x16x32_bf16 v[4:7], v[228:231], v[108:111], v[4:7]
	ds_read_b128 v[228:231], v212 offset:8896
	s_waitcnt lgkmcnt(4)
	v_mfma_f32_16x16x32_bf16 v[128:131], v[232:235], v[96:99], v[128:131]
	v_mfma_f32_16x16x32_bf16 v[4:7], v[232:235], v[100:103], v[4:7]
	ds_read_b128 v[232:235], v212 offset:16896
	s_waitcnt lgkmcnt(4)
	v_mfma_f32_16x16x32_bf16 v[128:131], v[236:239], v[88:91], v[128:131]
	v_mfma_f32_16x16x32_bf16 v[4:7], v[236:239], v[92:95], v[4:7]
	ds_read_b128 v[236:239], v212 offset:16960
	s_waitcnt lgkmcnt(4)
	v_mfma_f32_16x16x32_bf16 v[128:131], v[240:243], v[80:83], v[128:131]
	v_mfma_f32_16x16x32_bf16 v[4:7], v[240:243], v[84:87], v[4:7]
	ds_read_b128 v[240:243], v212 offset:17024
	s_waitcnt lgkmcnt(4)
	v_mfma_f32_16x16x32_bf16 v[128:131], v[244:247], v[68:71], v[128:131]
	v_mfma_f32_16x16x32_bf16 v[4:7], v[244:247], v[72:75], v[4:7]
	ds_read_b128 v[244:247], v212 offset:17088
	s_waitcnt lgkmcnt(4)
	v_mfma_f32_16x16x32_bf16 v[128:131], v[228:231], v[60:63], v[128:131]
	v_mfma_f32_16x16x32_bf16 v[4:7], v[228:231], v[76:79], v[4:7]
	ds_read_b128 v[228:231], v212 offset:17152
	s_waitcnt lgkmcnt(4)
	v_mfma_f32_16x16x32_bf16 v[132:135], v[232:235], v[112:115], 0
	v_mfma_f32_16x16x32_bf16 v[8:11], v[232:235], v[124:127], 0
	ds_read_b128 v[232:235], v212 offset:17216
	s_waitcnt lgkmcnt(4)
	v_mfma_f32_16x16x32_bf16 v[132:135], v[236:239], v[116:119], v[132:135]
	v_mfma_f32_16x16x32_bf16 v[8:11], v[236:239], v[120:123], v[8:11]
	ds_read_b128 v[236:239], v212 offset:17280
	s_waitcnt lgkmcnt(4)
	v_mfma_f32_16x16x32_bf16 v[132:135], v[240:243], v[104:107], v[132:135]
	v_mfma_f32_16x16x32_bf16 v[8:11], v[240:243], v[108:111], v[8:11]
	ds_read_b128 v[240:243], v212 offset:17344
	s_waitcnt lgkmcnt(4)
	v_mfma_f32_16x16x32_bf16 v[132:135], v[244:247], v[96:99], v[132:135]
	v_mfma_f32_16x16x32_bf16 v[8:11], v[244:247], v[100:103], v[8:11]
	ds_read_b128 v[244:247], v212 offset:25344
	s_waitcnt lgkmcnt(4)
	v_mfma_f32_16x16x32_bf16 v[132:135], v[228:231], v[88:91], v[132:135]
	v_mfma_f32_16x16x32_bf16 v[8:11], v[228:231], v[92:95], v[8:11]
	ds_read_b128 v[228:231], v212 offset:25408
	s_waitcnt lgkmcnt(4)
	v_mfma_f32_16x16x32_bf16 v[132:135], v[232:235], v[80:83], v[132:135]
	v_mfma_f32_16x16x32_bf16 v[8:11], v[232:235], v[84:87], v[8:11]
	ds_read_b128 v[232:235], v212 offset:25472
	s_waitcnt lgkmcnt(4)
	v_mfma_f32_16x16x32_bf16 v[132:135], v[236:239], v[68:71], v[132:135]
	v_mfma_f32_16x16x32_bf16 v[8:11], v[236:239], v[72:75], v[8:11]
	ds_read_b128 v[236:239], v212 offset:25536
	s_waitcnt lgkmcnt(4)
	v_mfma_f32_16x16x32_bf16 v[132:135], v[240:243], v[60:63], v[132:135]
	v_mfma_f32_16x16x32_bf16 v[8:11], v[240:243], v[76:79], v[8:11]
	ds_read_b128 v[240:243], v212 offset:25600
	s_waitcnt lgkmcnt(4)
	v_mfma_f32_16x16x32_bf16 v[136:139], v[244:247], v[112:115], 0
	v_mfma_f32_16x16x32_bf16 v[12:15], v[244:247], v[124:127], 0
	ds_read_b128 v[244:247], v212 offset:25664
	s_waitcnt lgkmcnt(4)
	v_mfma_f32_16x16x32_bf16 v[136:139], v[228:231], v[116:119], v[136:139]
	v_mfma_f32_16x16x32_bf16 v[12:15], v[228:231], v[120:123], v[12:15]
	ds_read_b128 v[228:231], v212 offset:25728
	s_waitcnt lgkmcnt(4)
	v_mfma_f32_16x16x32_bf16 v[136:139], v[232:235], v[104:107], v[136:139]
	v_mfma_f32_16x16x32_bf16 v[12:15], v[232:235], v[108:111], v[12:15]
	ds_read_b128 v[232:235], v212 offset:25792
	s_waitcnt lgkmcnt(4)
	v_mfma_f32_16x16x32_bf16 v[136:139], v[236:239], v[96:99], v[136:139]
	v_mfma_f32_16x16x32_bf16 v[12:15], v[236:239], v[100:103], v[12:15]
	ds_read_b128 v[236:239], v212 offset:33792
	s_waitcnt lgkmcnt(4)
	v_mfma_f32_16x16x32_bf16 v[136:139], v[240:243], v[88:91], v[136:139]
	v_mfma_f32_16x16x32_bf16 v[12:15], v[240:243], v[92:95], v[12:15]
	ds_read_b128 v[240:243], v212 offset:33856
	s_waitcnt lgkmcnt(4)
	v_mfma_f32_16x16x32_bf16 v[136:139], v[244:247], v[80:83], v[136:139]
	v_mfma_f32_16x16x32_bf16 v[12:15], v[244:247], v[84:87], v[12:15]
	ds_read_b128 v[244:247], v212 offset:33920
	s_waitcnt lgkmcnt(4)
	v_mfma_f32_16x16x32_bf16 v[136:139], v[228:231], v[68:71], v[136:139]
	v_mfma_f32_16x16x32_bf16 v[12:15], v[228:231], v[72:75], v[12:15]
	ds_read_b128 v[228:231], v212 offset:33984
	s_waitcnt lgkmcnt(4)
	v_mfma_f32_16x16x32_bf16 v[136:139], v[232:235], v[60:63], v[136:139]
	v_mfma_f32_16x16x32_bf16 v[12:15], v[232:235], v[76:79], v[12:15]
	ds_read_b128 v[232:235], v212 offset:34048
	s_waitcnt lgkmcnt(4)
	v_mfma_f32_16x16x32_bf16 v[140:143], v[236:239], v[112:115], 0
	v_mfma_f32_16x16x32_bf16 v[16:19], v[236:239], v[124:127], 0
	ds_read_b128 v[236:239], v212 offset:34112
	s_waitcnt lgkmcnt(4)
	v_mfma_f32_16x16x32_bf16 v[140:143], v[240:243], v[116:119], v[140:143]
	v_mfma_f32_16x16x32_bf16 v[16:19], v[240:243], v[120:123], v[16:19]
	ds_read_b128 v[240:243], v212 offset:34176
	s_waitcnt lgkmcnt(4)
	v_mfma_f32_16x16x32_bf16 v[140:143], v[244:247], v[104:107], v[140:143]
	v_mfma_f32_16x16x32_bf16 v[16:19], v[244:247], v[108:111], v[16:19]
	ds_read_b128 v[244:247], v212 offset:34240
	s_waitcnt lgkmcnt(4)
	v_mfma_f32_16x16x32_bf16 v[140:143], v[228:231], v[96:99], v[140:143]
	v_mfma_f32_16x16x32_bf16 v[16:19], v[228:231], v[100:103], v[16:19]
	ds_read_b128 v[228:231], v212 offset:42240
	s_waitcnt lgkmcnt(4)
	v_mfma_f32_16x16x32_bf16 v[140:143], v[232:235], v[88:91], v[140:143]
	v_mfma_f32_16x16x32_bf16 v[16:19], v[232:235], v[92:95], v[16:19]
	ds_read_b128 v[232:235], v212 offset:42304
	s_waitcnt lgkmcnt(4)
	v_mfma_f32_16x16x32_bf16 v[140:143], v[236:239], v[80:83], v[140:143]
	v_mfma_f32_16x16x32_bf16 v[16:19], v[236:239], v[84:87], v[16:19]
	ds_read_b128 v[236:239], v212 offset:42368
	s_waitcnt lgkmcnt(4)
	v_mfma_f32_16x16x32_bf16 v[140:143], v[240:243], v[68:71], v[140:143]
	v_mfma_f32_16x16x32_bf16 v[16:19], v[240:243], v[72:75], v[16:19]
	ds_read_b128 v[240:243], v212 offset:42432
	s_waitcnt lgkmcnt(4)
	v_mfma_f32_16x16x32_bf16 v[140:143], v[244:247], v[60:63], v[140:143]
	v_mfma_f32_16x16x32_bf16 v[16:19], v[244:247], v[76:79], v[16:19]
	ds_read_b128 v[244:247], v212 offset:42496
	s_waitcnt lgkmcnt(4)
	v_mfma_f32_16x16x32_bf16 v[144:147], v[228:231], v[112:115], 0
	v_mfma_f32_16x16x32_bf16 v[20:23], v[228:231], v[124:127], 0
	ds_read_b128 v[228:231], v212 offset:42560
	s_waitcnt lgkmcnt(4)
	v_mfma_f32_16x16x32_bf16 v[144:147], v[232:235], v[116:119], v[144:147]
	v_mfma_f32_16x16x32_bf16 v[20:23], v[232:235], v[120:123], v[20:23]
	ds_read_b128 v[232:235], v212 offset:42624
	s_waitcnt lgkmcnt(4)
	v_mfma_f32_16x16x32_bf16 v[144:147], v[236:239], v[104:107], v[144:147]
	v_mfma_f32_16x16x32_bf16 v[20:23], v[236:239], v[108:111], v[20:23]
	ds_read_b128 v[236:239], v212 offset:42688
	s_waitcnt lgkmcnt(4)
	v_mfma_f32_16x16x32_bf16 v[144:147], v[240:243], v[96:99], v[144:147]
	v_mfma_f32_16x16x32_bf16 v[20:23], v[240:243], v[100:103], v[20:23]
	ds_read_b128 v[240:243], v212 offset:50688
	s_waitcnt lgkmcnt(4)
	v_mfma_f32_16x16x32_bf16 v[144:147], v[244:247], v[88:91], v[144:147]
	v_mfma_f32_16x16x32_bf16 v[20:23], v[244:247], v[92:95], v[20:23]
	ds_read_b128 v[244:247], v212 offset:50752
	s_waitcnt lgkmcnt(4)
	v_mfma_f32_16x16x32_bf16 v[144:147], v[228:231], v[80:83], v[144:147]
	v_mfma_f32_16x16x32_bf16 v[20:23], v[228:231], v[84:87], v[20:23]
	ds_read_b128 v[228:231], v212 offset:50816
	s_waitcnt lgkmcnt(4)
	v_mfma_f32_16x16x32_bf16 v[144:147], v[232:235], v[68:71], v[144:147]
	v_mfma_f32_16x16x32_bf16 v[20:23], v[232:235], v[72:75], v[20:23]
	ds_read_b128 v[232:235], v212 offset:50880
	s_waitcnt lgkmcnt(4)
	v_mfma_f32_16x16x32_bf16 v[144:147], v[236:239], v[60:63], v[144:147]
	v_mfma_f32_16x16x32_bf16 v[20:23], v[236:239], v[76:79], v[20:23]
	ds_read_b128 v[236:239], v212 offset:50944
	s_waitcnt lgkmcnt(4)
	v_mfma_f32_16x16x32_bf16 v[148:151], v[240:243], v[112:115], 0
	v_mfma_f32_16x16x32_bf16 v[24:27], v[240:243], v[124:127], 0
	ds_read_b128 v[240:243], v212 offset:51008
	s_waitcnt lgkmcnt(4)
	v_mfma_f32_16x16x32_bf16 v[148:151], v[244:247], v[116:119], v[148:151]
	v_mfma_f32_16x16x32_bf16 v[24:27], v[244:247], v[120:123], v[24:27]
	ds_read_b128 v[244:247], v212 offset:51072
	s_waitcnt lgkmcnt(4)
	v_mfma_f32_16x16x32_bf16 v[148:151], v[228:231], v[104:107], v[148:151]
	v_mfma_f32_16x16x32_bf16 v[24:27], v[228:231], v[108:111], v[24:27]
	ds_read_b128 v[228:231], v212 offset:51136
	s_waitcnt lgkmcnt(4)
	v_mfma_f32_16x16x32_bf16 v[148:151], v[232:235], v[96:99], v[148:151]
	v_mfma_f32_16x16x32_bf16 v[24:27], v[232:235], v[100:103], v[24:27]
	ds_read_b128 v[232:235], v212 offset:59136
	s_waitcnt lgkmcnt(4)
	v_mfma_f32_16x16x32_bf16 v[148:151], v[236:239], v[88:91], v[148:151]
	v_mfma_f32_16x16x32_bf16 v[24:27], v[236:239], v[92:95], v[24:27]
	ds_read_b128 v[236:239], v212 offset:59200
	s_waitcnt lgkmcnt(4)
	v_mfma_f32_16x16x32_bf16 v[148:151], v[240:243], v[80:83], v[148:151]
	v_mfma_f32_16x16x32_bf16 v[24:27], v[240:243], v[84:87], v[24:27]
	ds_read_b128 v[240:243], v212 offset:59264
	s_waitcnt lgkmcnt(4)
	v_mfma_f32_16x16x32_bf16 v[148:151], v[244:247], v[68:71], v[148:151]
	v_mfma_f32_16x16x32_bf16 v[24:27], v[244:247], v[72:75], v[24:27]
	ds_read_b128 v[244:247], v212 offset:59328
	s_waitcnt lgkmcnt(4)
	v_mfma_f32_16x16x32_bf16 v[148:151], v[228:231], v[60:63], v[148:151]
	v_mfma_f32_16x16x32_bf16 v[24:27], v[228:231], v[76:79], v[24:27]
	ds_read_b128 v[228:231], v212 offset:59392
	s_waitcnt lgkmcnt(4)
	v_mfma_f32_16x16x32_bf16 v[152:155], v[232:235], v[112:115], 0
	v_mfma_f32_16x16x32_bf16 v[28:31], v[232:235], v[124:127], 0
	ds_read_b128 v[232:235], v212 offset:59456
	s_waitcnt lgkmcnt(4)
	v_mfma_f32_16x16x32_bf16 v[152:155], v[236:239], v[116:119], v[152:155]
	v_mfma_f32_16x16x32_bf16 v[28:31], v[236:239], v[120:123], v[28:31]
	ds_read_b128 v[236:239], v212 offset:59520
	s_waitcnt lgkmcnt(4)
	v_mfma_f32_16x16x32_bf16 v[152:155], v[240:243], v[104:107], v[152:155]
	v_mfma_f32_16x16x32_bf16 v[28:31], v[240:243], v[108:111], v[28:31]
	ds_read_b128 v[240:243], v212 offset:59584
	s_waitcnt lgkmcnt(4)
	v_mfma_f32_16x16x32_bf16 v[152:155], v[244:247], v[96:99], v[152:155]
	v_mfma_f32_16x16x32_bf16 v[28:31], v[244:247], v[100:103], v[28:31]
	ds_read_b128 v[244:247], v215
	s_waitcnt lgkmcnt(4)
	v_mfma_f32_16x16x32_bf16 v[152:155], v[228:231], v[88:91], v[152:155]
	v_mfma_f32_16x16x32_bf16 v[28:31], v[228:231], v[92:95], v[28:31]
	ds_read_b128 v[228:231], v215 offset:64
	s_waitcnt lgkmcnt(4)
	v_mfma_f32_16x16x32_bf16 v[152:155], v[232:235], v[80:83], v[152:155]
	v_mfma_f32_16x16x32_bf16 v[28:31], v[232:235], v[84:87], v[28:31]
	ds_read_b128 v[232:235], v215 offset:128
	s_waitcnt lgkmcnt(4)
	v_mfma_f32_16x16x32_bf16 v[152:155], v[236:239], v[68:71], v[152:155]
	v_mfma_f32_16x16x32_bf16 v[28:31], v[236:239], v[72:75], v[28:31]
	ds_read_b128 v[236:239], v215 offset:192
	s_waitcnt lgkmcnt(4)
	v_mfma_f32_16x16x32_bf16 v[152:155], v[240:243], v[60:63], v[152:155]
	v_mfma_f32_16x16x32_bf16 v[28:31], v[240:243], v[76:79], v[28:31]
	ds_read_b128 v[240:243], v215 offset:256
	s_waitcnt lgkmcnt(4)
	v_mfma_f32_16x16x32_bf16 v[156:159], v[244:247], v[112:115], 0
	v_mfma_f32_16x16x32_bf16 v[32:35], v[244:247], v[124:127], 0
	ds_read_b128 v[244:247], v215 offset:320
	s_waitcnt lgkmcnt(4)
	v_mfma_f32_16x16x32_bf16 v[156:159], v[228:231], v[116:119], v[156:159]
	v_mfma_f32_16x16x32_bf16 v[32:35], v[228:231], v[120:123], v[32:35]
	ds_read_b128 v[228:231], v215 offset:384
	s_waitcnt lgkmcnt(4)
	v_mfma_f32_16x16x32_bf16 v[156:159], v[232:235], v[104:107], v[156:159]
	v_mfma_f32_16x16x32_bf16 v[32:35], v[232:235], v[108:111], v[32:35]
	ds_read_b128 v[232:235], v215 offset:448
	s_waitcnt lgkmcnt(4)
	v_mfma_f32_16x16x32_bf16 v[156:159], v[236:239], v[96:99], v[156:159]
	v_mfma_f32_16x16x32_bf16 v[32:35], v[236:239], v[100:103], v[32:35]
	ds_read_b128 v[236:239], v215 offset:8448
	s_waitcnt lgkmcnt(4)
	v_mfma_f32_16x16x32_bf16 v[156:159], v[240:243], v[88:91], v[156:159]
	v_mfma_f32_16x16x32_bf16 v[32:35], v[240:243], v[92:95], v[32:35]
	ds_read_b128 v[240:243], v215 offset:8512
	s_waitcnt lgkmcnt(4)
	v_mfma_f32_16x16x32_bf16 v[156:159], v[244:247], v[80:83], v[156:159]
	v_mfma_f32_16x16x32_bf16 v[32:35], v[244:247], v[84:87], v[32:35]
	ds_read_b128 v[244:247], v215 offset:8576
	s_waitcnt lgkmcnt(4)
	v_mfma_f32_16x16x32_bf16 v[156:159], v[228:231], v[68:71], v[156:159]
	v_mfma_f32_16x16x32_bf16 v[32:35], v[228:231], v[72:75], v[32:35]
	ds_read_b128 v[228:231], v215 offset:8640
	s_waitcnt lgkmcnt(4)
	v_mfma_f32_16x16x32_bf16 v[156:159], v[232:235], v[60:63], v[156:159]
	v_mfma_f32_16x16x32_bf16 v[32:35], v[232:235], v[76:79], v[32:35]
	ds_read_b128 v[232:235], v215 offset:8704
	s_waitcnt lgkmcnt(4)
	v_mfma_f32_16x16x32_bf16 v[160:163], v[236:239], v[112:115], 0
	v_mfma_f32_16x16x32_bf16 v[36:39], v[236:239], v[124:127], 0
	ds_read_b128 v[236:239], v215 offset:8768
	s_waitcnt lgkmcnt(4)
	v_mfma_f32_16x16x32_bf16 v[160:163], v[240:243], v[116:119], v[160:163]
	v_mfma_f32_16x16x32_bf16 v[36:39], v[240:243], v[120:123], v[36:39]
	ds_read_b128 v[240:243], v215 offset:8832
	s_waitcnt lgkmcnt(4)
	v_mfma_f32_16x16x32_bf16 v[160:163], v[244:247], v[104:107], v[160:163]
	v_mfma_f32_16x16x32_bf16 v[36:39], v[244:247], v[108:111], v[36:39]
	ds_read_b128 v[244:247], v215 offset:8896
	s_waitcnt lgkmcnt(4)
	v_mfma_f32_16x16x32_bf16 v[160:163], v[228:231], v[96:99], v[160:163]
	v_mfma_f32_16x16x32_bf16 v[36:39], v[228:231], v[100:103], v[36:39]
	ds_read_b128 v[228:231], v215 offset:16896
	s_waitcnt lgkmcnt(4)
	v_mfma_f32_16x16x32_bf16 v[160:163], v[232:235], v[88:91], v[160:163]
	v_mfma_f32_16x16x32_bf16 v[36:39], v[232:235], v[92:95], v[36:39]
	ds_read_b128 v[232:235], v215 offset:16960
	s_waitcnt lgkmcnt(4)
	v_mfma_f32_16x16x32_bf16 v[160:163], v[236:239], v[80:83], v[160:163]
	v_mfma_f32_16x16x32_bf16 v[36:39], v[236:239], v[84:87], v[36:39]
	ds_read_b128 v[236:239], v215 offset:17024
	s_waitcnt lgkmcnt(4)
	v_mfma_f32_16x16x32_bf16 v[160:163], v[240:243], v[68:71], v[160:163]
	v_mfma_f32_16x16x32_bf16 v[36:39], v[240:243], v[72:75], v[36:39]
	ds_read_b128 v[240:243], v215 offset:17088
	s_waitcnt lgkmcnt(4)
	v_mfma_f32_16x16x32_bf16 v[160:163], v[244:247], v[60:63], v[160:163]
	v_mfma_f32_16x16x32_bf16 v[36:39], v[244:247], v[76:79], v[36:39]
	ds_read_b128 v[244:247], v215 offset:17152
	s_waitcnt lgkmcnt(4)
	v_mfma_f32_16x16x32_bf16 v[164:167], v[228:231], v[112:115], 0
	v_mfma_f32_16x16x32_bf16 v[40:43], v[228:231], v[124:127], 0
	ds_read_b128 v[228:231], v215 offset:17216
	s_waitcnt lgkmcnt(4)
	v_mfma_f32_16x16x32_bf16 v[164:167], v[232:235], v[116:119], v[164:167]
	v_mfma_f32_16x16x32_bf16 v[40:43], v[232:235], v[120:123], v[40:43]
	ds_read_b128 v[232:235], v215 offset:17280
	s_waitcnt lgkmcnt(4)
	v_mfma_f32_16x16x32_bf16 v[164:167], v[236:239], v[104:107], v[164:167]
	v_mfma_f32_16x16x32_bf16 v[40:43], v[236:239], v[108:111], v[40:43]
	ds_read_b128 v[236:239], v215 offset:17344
	s_waitcnt lgkmcnt(4)
	v_mfma_f32_16x16x32_bf16 v[164:167], v[240:243], v[96:99], v[164:167]
	v_mfma_f32_16x16x32_bf16 v[40:43], v[240:243], v[100:103], v[40:43]
	ds_read_b128 v[240:243], v215 offset:25344
	s_waitcnt lgkmcnt(4)
	v_mfma_f32_16x16x32_bf16 v[164:167], v[244:247], v[88:91], v[164:167]
	v_mfma_f32_16x16x32_bf16 v[40:43], v[244:247], v[92:95], v[40:43]
	ds_read_b128 v[244:247], v215 offset:25408
	s_waitcnt lgkmcnt(4)
	v_mfma_f32_16x16x32_bf16 v[164:167], v[228:231], v[80:83], v[164:167]
	v_mfma_f32_16x16x32_bf16 v[40:43], v[228:231], v[84:87], v[40:43]
	ds_read_b128 v[228:231], v215 offset:25472
	s_waitcnt lgkmcnt(4)
	v_mfma_f32_16x16x32_bf16 v[164:167], v[232:235], v[68:71], v[164:167]
	v_mfma_f32_16x16x32_bf16 v[40:43], v[232:235], v[72:75], v[40:43]
	ds_read_b128 v[232:235], v215 offset:25536
	s_waitcnt lgkmcnt(4)
	v_mfma_f32_16x16x32_bf16 v[164:167], v[236:239], v[60:63], v[164:167]
	v_mfma_f32_16x16x32_bf16 v[40:43], v[236:239], v[76:79], v[40:43]
	ds_read_b128 v[236:239], v215 offset:25600
	s_waitcnt lgkmcnt(4)
	v_mfma_f32_16x16x32_bf16 v[168:171], v[240:243], v[112:115], 0
	v_mfma_f32_16x16x32_bf16 v[44:47], v[240:243], v[124:127], 0
	ds_read_b128 v[240:243], v215 offset:25664
	s_waitcnt lgkmcnt(4)
	v_mfma_f32_16x16x32_bf16 v[168:171], v[244:247], v[116:119], v[168:171]
	v_mfma_f32_16x16x32_bf16 v[44:47], v[244:247], v[120:123], v[44:47]
	ds_read_b128 v[244:247], v215 offset:25728
	s_waitcnt lgkmcnt(4)
	v_mfma_f32_16x16x32_bf16 v[168:171], v[228:231], v[104:107], v[168:171]
	v_mfma_f32_16x16x32_bf16 v[44:47], v[228:231], v[108:111], v[44:47]
	ds_read_b128 v[228:231], v215 offset:25792
	s_waitcnt lgkmcnt(4)
	v_mfma_f32_16x16x32_bf16 v[168:171], v[232:235], v[96:99], v[168:171]
	v_mfma_f32_16x16x32_bf16 v[44:47], v[232:235], v[100:103], v[44:47]
	ds_read_b128 v[232:235], v215 offset:33792
	s_waitcnt lgkmcnt(4)
	v_mfma_f32_16x16x32_bf16 v[168:171], v[236:239], v[88:91], v[168:171]
	v_mfma_f32_16x16x32_bf16 v[44:47], v[236:239], v[92:95], v[44:47]
	ds_read_b128 v[236:239], v215 offset:33856
	s_waitcnt lgkmcnt(4)
	v_mfma_f32_16x16x32_bf16 v[168:171], v[240:243], v[80:83], v[168:171]
	v_mfma_f32_16x16x32_bf16 v[44:47], v[240:243], v[84:87], v[44:47]
	ds_read_b128 v[240:243], v215 offset:33920
	s_waitcnt lgkmcnt(4)
	v_mfma_f32_16x16x32_bf16 v[168:171], v[244:247], v[68:71], v[168:171]
	v_mfma_f32_16x16x32_bf16 v[44:47], v[244:247], v[72:75], v[44:47]
	ds_read_b128 v[244:247], v215 offset:33984
	s_waitcnt lgkmcnt(4)
	v_mfma_f32_16x16x32_bf16 v[168:171], v[228:231], v[60:63], v[168:171]
	v_mfma_f32_16x16x32_bf16 v[44:47], v[228:231], v[76:79], v[44:47]
	ds_read_b128 v[228:231], v215 offset:34048
	s_waitcnt lgkmcnt(4)
	v_mfma_f32_16x16x32_bf16 v[172:175], v[232:235], v[112:115], 0
	v_mfma_f32_16x16x32_bf16 v[48:51], v[232:235], v[124:127], 0
	ds_read_b128 v[232:235], v215 offset:34112
	s_waitcnt lgkmcnt(4)
	v_mfma_f32_16x16x32_bf16 v[172:175], v[236:239], v[116:119], v[172:175]
	v_mfma_f32_16x16x32_bf16 v[48:51], v[236:239], v[120:123], v[48:51]
	ds_read_b128 v[236:239], v215 offset:34176
	s_waitcnt lgkmcnt(4)
	v_mfma_f32_16x16x32_bf16 v[172:175], v[240:243], v[104:107], v[172:175]
	v_mfma_f32_16x16x32_bf16 v[48:51], v[240:243], v[108:111], v[48:51]
	ds_read_b128 v[240:243], v215 offset:34240
	s_waitcnt lgkmcnt(4)
	v_mfma_f32_16x16x32_bf16 v[172:175], v[244:247], v[96:99], v[172:175]
	v_mfma_f32_16x16x32_bf16 v[48:51], v[244:247], v[100:103], v[48:51]
	ds_read_b128 v[244:247], v215 offset:42240
	s_waitcnt lgkmcnt(4)
	v_mfma_f32_16x16x32_bf16 v[172:175], v[228:231], v[88:91], v[172:175]
	v_mfma_f32_16x16x32_bf16 v[48:51], v[228:231], v[92:95], v[48:51]
	ds_read_b128 v[228:231], v215 offset:42304
	s_waitcnt lgkmcnt(4)
	v_mfma_f32_16x16x32_bf16 v[172:175], v[232:235], v[80:83], v[172:175]
	v_mfma_f32_16x16x32_bf16 v[48:51], v[232:235], v[84:87], v[48:51]
	ds_read_b128 v[232:235], v215 offset:42368
	s_waitcnt lgkmcnt(4)
	v_mfma_f32_16x16x32_bf16 v[172:175], v[236:239], v[68:71], v[172:175]
	v_mfma_f32_16x16x32_bf16 v[48:51], v[236:239], v[72:75], v[48:51]
	ds_read_b128 v[236:239], v215 offset:42432
	s_waitcnt lgkmcnt(4)
	v_mfma_f32_16x16x32_bf16 v[172:175], v[240:243], v[60:63], v[172:175]
	v_mfma_f32_16x16x32_bf16 v[48:51], v[240:243], v[76:79], v[48:51]
	ds_read_b128 v[240:243], v215 offset:42496
	s_waitcnt lgkmcnt(4)
	v_mfma_f32_16x16x32_bf16 v[176:179], v[244:247], v[112:115], 0
	v_mfma_f32_16x16x32_bf16 v[52:55], v[244:247], v[124:127], 0
	ds_read_b128 v[244:247], v215 offset:42560
	s_waitcnt lgkmcnt(4)
	v_mfma_f32_16x16x32_bf16 v[176:179], v[228:231], v[116:119], v[176:179]
	v_mfma_f32_16x16x32_bf16 v[52:55], v[228:231], v[120:123], v[52:55]
	ds_read_b128 v[228:231], v215 offset:42624
	s_waitcnt lgkmcnt(4)
	v_mfma_f32_16x16x32_bf16 v[176:179], v[232:235], v[104:107], v[176:179]
	v_mfma_f32_16x16x32_bf16 v[52:55], v[232:235], v[108:111], v[52:55]
	ds_read_b128 v[232:235], v215 offset:42688
	s_waitcnt lgkmcnt(4)
	v_mfma_f32_16x16x32_bf16 v[176:179], v[236:239], v[96:99], v[176:179]
	v_mfma_f32_16x16x32_bf16 v[52:55], v[236:239], v[100:103], v[52:55]
	ds_read_b128 v[236:239], v215 offset:50688
	s_waitcnt lgkmcnt(4)
	v_mfma_f32_16x16x32_bf16 v[176:179], v[240:243], v[88:91], v[176:179]
	v_mfma_f32_16x16x32_bf16 v[52:55], v[240:243], v[92:95], v[52:55]
	ds_read_b128 v[240:243], v215 offset:50752
	s_waitcnt lgkmcnt(4)
	v_mfma_f32_16x16x32_bf16 v[176:179], v[244:247], v[80:83], v[176:179]
	v_mfma_f32_16x16x32_bf16 v[52:55], v[244:247], v[84:87], v[52:55]
	ds_read_b128 v[244:247], v215 offset:50816
	s_waitcnt lgkmcnt(4)
	v_mfma_f32_16x16x32_bf16 v[176:179], v[228:231], v[68:71], v[176:179]
	v_mfma_f32_16x16x32_bf16 v[52:55], v[228:231], v[72:75], v[52:55]
	ds_read_b128 v[228:231], v215 offset:50880
	s_waitcnt lgkmcnt(4)
	v_mfma_f32_16x16x32_bf16 v[176:179], v[232:235], v[60:63], v[176:179]
	v_mfma_f32_16x16x32_bf16 v[52:55], v[232:235], v[76:79], v[52:55]
	ds_read_b128 v[232:235], v215 offset:50944
	s_waitcnt lgkmcnt(4)
	v_mfma_f32_16x16x32_bf16 v[180:183], v[236:239], v[112:115], 0
	v_mfma_f32_16x16x32_bf16 v[56:59], v[236:239], v[124:127], 0
	ds_read_b128 v[236:239], v215 offset:51008
	s_waitcnt lgkmcnt(4)
	v_mfma_f32_16x16x32_bf16 v[180:183], v[240:243], v[116:119], v[180:183]
	v_mfma_f32_16x16x32_bf16 v[56:59], v[240:243], v[120:123], v[56:59]
	ds_read_b128 v[240:243], v215 offset:51072
	s_waitcnt lgkmcnt(4)
	v_mfma_f32_16x16x32_bf16 v[180:183], v[244:247], v[104:107], v[180:183]
	v_mfma_f32_16x16x32_bf16 v[56:59], v[244:247], v[108:111], v[56:59]
	ds_read_b128 v[244:247], v215 offset:51136
	s_waitcnt lgkmcnt(4)
	v_mfma_f32_16x16x32_bf16 v[180:183], v[228:231], v[96:99], v[180:183]
	v_mfma_f32_16x16x32_bf16 v[56:59], v[228:231], v[100:103], v[56:59]
	ds_read_b128 v[228:231], v215 offset:59136
	s_waitcnt lgkmcnt(4)
	v_mfma_f32_16x16x32_bf16 v[180:183], v[232:235], v[88:91], v[180:183]
	v_mfma_f32_16x16x32_bf16 v[56:59], v[232:235], v[92:95], v[56:59]
	ds_read_b128 v[232:235], v215 offset:59200
	s_waitcnt lgkmcnt(4)
	v_mfma_f32_16x16x32_bf16 v[180:183], v[236:239], v[80:83], v[180:183]
	v_mfma_f32_16x16x32_bf16 v[56:59], v[236:239], v[84:87], v[56:59]
	ds_read_b128 v[236:239], v215 offset:59264
	s_waitcnt lgkmcnt(4)
	v_mfma_f32_16x16x32_bf16 v[180:183], v[240:243], v[68:71], v[180:183]
	v_mfma_f32_16x16x32_bf16 v[56:59], v[240:243], v[72:75], v[56:59]
	ds_read_b128 v[240:243], v215 offset:59328
	s_waitcnt lgkmcnt(4)
	v_mfma_f32_16x16x32_bf16 v[180:183], v[244:247], v[60:63], v[180:183]
	v_mfma_f32_16x16x32_bf16 v[56:59], v[244:247], v[76:79], v[56:59]
	ds_read_b128 v[244:247], v215 offset:59392
	s_waitcnt lgkmcnt(4)
	v_mfma_f32_16x16x32_bf16 v[224:227], v[228:231], v[112:115], 0
	v_mfma_f32_16x16x32_bf16 v[248:251], v[228:231], v[124:127], 0
	ds_read_b128 v[228:231], v215 offset:59456
	s_waitcnt lgkmcnt(4)
	v_mfma_f32_16x16x32_bf16 v[224:227], v[232:235], v[116:119], v[224:227]
	v_mfma_f32_16x16x32_bf16 v[248:251], v[232:235], v[120:123], v[248:251]
	ds_read_b128 v[232:235], v215 offset:59520
	s_waitcnt lgkmcnt(4)
	v_mfma_f32_16x16x32_bf16 v[224:227], v[236:239], v[104:107], v[224:227]
	v_mfma_f32_16x16x32_bf16 v[248:251], v[236:239], v[108:111], v[248:251]
	ds_read_b128 v[236:239], v215 offset:59584
	s_waitcnt lgkmcnt(4)
	v_mfma_f32_16x16x32_bf16 v[224:227], v[240:243], v[96:99], v[224:227]
	v_mfma_f32_16x16x32_bf16 v[248:251], v[240:243], v[100:103], v[248:251]
	s_waitcnt lgkmcnt(3)
	v_mfma_f32_16x16x32_bf16 v[224:227], v[244:247], v[88:91], v[224:227]
	v_mfma_f32_16x16x32_bf16 v[248:251], v[244:247], v[92:95], v[248:251]
	s_waitcnt lgkmcnt(2)
	v_mfma_f32_16x16x32_bf16 v[224:227], v[228:231], v[80:83], v[224:227]
	v_mfma_f32_16x16x32_bf16 v[248:251], v[228:231], v[84:87], v[248:251]
	s_waitcnt lgkmcnt(1)
	v_mfma_f32_16x16x32_bf16 v[224:227], v[232:235], v[68:71], v[224:227]
	v_mfma_f32_16x16x32_bf16 v[248:251], v[232:235], v[72:75], v[248:251]
	s_waitcnt lgkmcnt(0)
	v_mfma_f32_16x16x32_bf16 v[68:71], v[236:239], v[60:63], v[224:227]
	v_mfma_f32_16x16x32_bf16 v[60:63], v[236:239], v[76:79], v[248:251]
	s_barrier
	v_or_b32_e32 v252, s7, v187
	v_lshlrev_b32_e32 v252, 12, v252
	v_add_u32_e32 v252, v252, v190
	s_lshl_b32 s14, s6, 1
	s_add_u32 s14, s12, s14
	s_addc_u32 s15, s13, 0
	global_load_dwordx4 v[224:227], v252, s[14:15]
	s_add_u32 s14, s14, 0x10000
	s_addc_u32 s15, s15, 0
	global_load_dwordx4 v[228:231], v252, s[14:15]
	s_add_u32 s14, s14, 0x10000
	s_addc_u32 s15, s15, 0
	global_load_dwordx4 v[232:235], v252, s[14:15]
	s_add_u32 s14, s14, 0x10000
	s_addc_u32 s15, s15, 0
	global_load_dwordx4 v[236:239], v252, s[14:15]
	s_add_u32 s14, s14, 0x10000
	s_addc_u32 s15, s15, 0
	global_load_dwordx4 v[240:243], v252, s[14:15]
	s_add_u32 s14, s14, 0x10000
	s_addc_u32 s15, s15, 0
	global_load_dwordx4 v[244:247], v252, s[14:15]
	s_add_u32 s14, s14, 0x10000
	s_addc_u32 s15, s15, 0
	global_load_dwordx4 v[248:251], v252, s[14:15]
	s_add_u32 s14, s14, 0x10000
	s_addc_u32 s15, s15, 0
	v_max_f32_e32 v72, v65, v65
	v_max_f32_e32 v73, v64, v64
	v_max_f32_e32 v72, v73, v72
	v_max3_f32 v72, v72, v66, v67
	v_max3_f32 v72, v72, v128, v129
	v_max3_f32 v72, v72, v130, v131
	v_max3_f32 v72, v72, v132, v133
	v_max3_f32 v72, v72, v134, v135
	v_max3_f32 v72, v72, v136, v137
	v_max3_f32 v72, v72, v138, v139
	v_max3_f32 v72, v72, v140, v141
	v_max3_f32 v72, v72, v142, v143
	v_max3_f32 v72, v72, v144, v145
	v_max3_f32 v72, v72, v146, v147
	v_max3_f32 v72, v72, v148, v149
	v_max3_f32 v72, v72, v150, v151
	v_max3_f32 v72, v72, v152, v153
	v_max3_f32 v72, v72, v154, v155
	v_max3_f32 v72, v72, v156, v157
	v_max3_f32 v72, v72, v158, v159
	v_max3_f32 v72, v72, v160, v161
	v_max3_f32 v72, v72, v162, v163
	v_max3_f32 v72, v72, v164, v165
	v_max3_f32 v72, v72, v166, v167
	v_max3_f32 v72, v72, v168, v169
	v_max3_f32 v72, v72, v170, v171
	v_max3_f32 v72, v72, v172, v173
	v_max3_f32 v72, v72, v174, v175
	v_max3_f32 v72, v72, v176, v177
	v_max3_f32 v72, v72, v178, v179
	v_max3_f32 v72, v72, v180, v181
	v_max3_f32 v72, v72, v182, v183
	v_max3_f32 v72, v72, v68, v69
	v_max3_f32 v72, v72, v70, v71
	ds_bpermute_b32 v73, v198, v72
	s_waitcnt lgkmcnt(0)
	v_max_f32_e32 v73, v73, v73
	v_max_f32_e32 v72, v72, v73
	ds_bpermute_b32 v73, v199, v72
	s_waitcnt lgkmcnt(0)
	v_max_f32_e32 v73, v73, v73
	v_max_f32_e32 v223, v72, v73
	v_sub_f32_e32 v64, v64, v223
	v_mul_f32_e32 v64, 0x3d800000, v64
	v_sub_f32_e32 v65, v65, v223
	v_mul_f32_e32 v64, 0x3fb8aa3b, v64
	v_mul_f32_e32 v65, 0x3d800000, v65
	v_sub_f32_e32 v66, v66, v223
	v_exp_f32_e32 v64, v64
	v_mul_f32_e32 v65, 0x3fb8aa3b, v65
	v_mul_f32_e32 v66, 0x3d800000, v66
	v_sub_f32_e32 v67, v67, v223
	v_exp_f32_e32 v65, v65
	v_mul_f32_e32 v66, 0x3fb8aa3b, v66
	v_mul_f32_e32 v67, 0x3d800000, v67
	v_exp_f32_e32 v66, v66
	v_mul_f32_e32 v67, 0x3fb8aa3b, v67
	v_exp_f32_e32 v67, v67
	v_add_f32_e32 v72, 0, v64
	v_add_f32_e32 v72, v65, v72
	v_add_f32_e32 v72, v66, v72
	v_add_f32_e32 v73, v67, v72
	v_sub_f32_e32 v72, v128, v223
	v_mul_f32_e32 v72, 0x3d800000, v72
	v_mul_f32_e32 v72, 0x3fb8aa3b, v72
	v_exp_f32_e32 v72, v72
	v_sub_f32_e32 v95, v150, v223
	v_mul_f32_e32 v95, 0x3d800000, v95
	v_mul_f32_e32 v95, 0x3fb8aa3b, v95
	v_add_f32_e32 v74, v72, v73
	v_sub_f32_e32 v73, v129, v223
	v_mul_f32_e32 v73, 0x3d800000, v73
	v_mul_f32_e32 v73, 0x3fb8aa3b, v73
	v_exp_f32_e32 v73, v73
	v_exp_f32_e32 v96, v95
	v_sub_f32_e32 v95, v151, v223
	v_mul_f32_e32 v95, 0x3d800000, v95
	v_add_f32_e32 v75, v73, v74
	v_sub_f32_e32 v74, v130, v223
	v_mul_f32_e32 v74, 0x3d800000, v74
	v_mul_f32_e32 v74, 0x3fb8aa3b, v74
	v_exp_f32_e32 v74, v74
	v_mul_f32_e32 v95, 0x3fb8aa3b, v95
	v_exp_f32_e32 v97, v95
	v_sub_f32_e32 v95, v152, v223
	v_add_f32_e32 v76, v74, v75
	v_sub_f32_e32 v75, v131, v223
	v_mul_f32_e32 v75, 0x3d800000, v75
	v_mul_f32_e32 v75, 0x3fb8aa3b, v75
	v_exp_f32_e32 v75, v75
	v_mul_f32_e32 v95, 0x3d800000, v95
	v_mul_f32_e32 v95, 0x3fb8aa3b, v95
	v_exp_f32_e32 v99, v95
	v_add_f32_e32 v77, v75, v76
	v_sub_f32_e32 v76, v132, v223
	v_mul_f32_e32 v76, 0x3d800000, v76
	v_mul_f32_e32 v76, 0x3fb8aa3b, v76
	v_exp_f32_e32 v76, v76
	v_sub_f32_e32 v95, v153, v223
	v_mul_f32_e32 v95, 0x3d800000, v95
	v_mul_f32_e32 v95, 0x3fb8aa3b, v95
	v_add_f32_e32 v78, v76, v77
	v_sub_f32_e32 v77, v133, v223
	v_mul_f32_e32 v77, 0x3d800000, v77
	v_mul_f32_e32 v77, 0x3fb8aa3b, v77
	v_exp_f32_e32 v77, v77
	v_exp_f32_e32 v101, v95
	v_sub_f32_e32 v95, v154, v223
	v_mul_f32_e32 v95, 0x3d800000, v95
	v_add_f32_e32 v79, v77, v78
	v_sub_f32_e32 v78, v134, v223
	v_mul_f32_e32 v78, 0x3d800000, v78
	v_mul_f32_e32 v78, 0x3fb8aa3b, v78
	v_exp_f32_e32 v78, v78
	v_mul_f32_e32 v95, 0x3fb8aa3b, v95
	v_exp_f32_e32 v104, v95
	v_sub_f32_e32 v95, v155, v223
	v_add_f32_e32 v80, v78, v79
	v_sub_f32_e32 v79, v135, v223
	v_mul_f32_e32 v79, 0x3d800000, v79
	v_mul_f32_e32 v79, 0x3fb8aa3b, v79
	v_exp_f32_e32 v79, v79
	v_mul_f32_e32 v95, 0x3d800000, v95
	v_mul_f32_e32 v95, 0x3fb8aa3b, v95
	v_exp_f32_e32 v105, v95
	v_add_f32_e32 v81, v79, v80
	v_sub_f32_e32 v80, v136, v223
	v_mul_f32_e32 v80, 0x3d800000, v80
	v_mul_f32_e32 v80, 0x3fb8aa3b, v80
	v_exp_f32_e32 v80, v80
	v_sub_f32_e32 v95, v156, v223
	v_mul_f32_e32 v95, 0x3d800000, v95
	v_mul_f32_e32 v95, 0x3fb8aa3b, v95
	v_add_f32_e32 v82, v80, v81
	v_sub_f32_e32 v81, v137, v223
	v_mul_f32_e32 v81, 0x3d800000, v81
	v_mul_f32_e32 v81, 0x3fb8aa3b, v81
	v_exp_f32_e32 v81, v81
	v_exp_f32_e32 v107, v95
	v_sub_f32_e32 v95, v157, v223
	v_mul_f32_e32 v95, 0x3d800000, v95
	v_add_f32_e32 v83, v81, v82
	v_sub_f32_e32 v82, v138, v223
	v_mul_f32_e32 v82, 0x3d800000, v82
	v_mul_f32_e32 v82, 0x3fb8aa3b, v82
	v_exp_f32_e32 v82, v82
	v_mul_f32_e32 v95, 0x3fb8aa3b, v95
	v_exp_f32_e32 v109, v95
	v_sub_f32_e32 v95, v158, v223
	v_add_f32_e32 v84, v82, v83
	v_sub_f32_e32 v83, v139, v223
	v_mul_f32_e32 v83, 0x3d800000, v83
	v_mul_f32_e32 v83, 0x3fb8aa3b, v83
	v_exp_f32_e32 v83, v83
	v_mul_f32_e32 v95, 0x3d800000, v95
	v_mul_f32_e32 v95, 0x3fb8aa3b, v95
	v_exp_f32_e32 v112, v95
	v_add_f32_e32 v85, v83, v84
	v_sub_f32_e32 v84, v140, v223
	v_mul_f32_e32 v84, 0x3d800000, v84
	v_mul_f32_e32 v84, 0x3fb8aa3b, v84
	v_exp_f32_e32 v84, v84
	v_sub_f32_e32 v95, v159, v223
	v_mul_f32_e32 v95, 0x3d800000, v95
	v_mul_f32_e32 v95, 0x3fb8aa3b, v95
	v_add_f32_e32 v86, v84, v85
	v_sub_f32_e32 v85, v141, v223
	v_mul_f32_e32 v85, 0x3d800000, v85
	v_mul_f32_e32 v85, 0x3fb8aa3b, v85
	v_exp_f32_e32 v85, v85
	v_exp_f32_e32 v113, v95
	v_sub_f32_e32 v116, v171, v223
	v_mul_f32_e32 v116, 0x3d800000, v116
	v_add_f32_e32 v87, v85, v86
	v_sub_f32_e32 v86, v142, v223
	v_mul_f32_e32 v86, 0x3d800000, v86
	v_mul_f32_e32 v86, 0x3fb8aa3b, v86
	v_exp_f32_e32 v86, v86
	v_mul_f32_e32 v116, 0x3fb8aa3b, v116
	v_exp_f32_e32 v116, v116
	v_sub_f32_e32 v118, v173, v223
	v_add_f32_e32 v88, v86, v87
	v_sub_f32_e32 v87, v143, v223
	v_mul_f32_e32 v87, 0x3d800000, v87
	v_mul_f32_e32 v87, 0x3fb8aa3b, v87
	v_exp_f32_e32 v87, v87
	v_mul_f32_e32 v118, 0x3d800000, v118
	v_mul_f32_e32 v118, 0x3fb8aa3b, v118
	v_exp_f32_e32 v118, v118
	v_add_f32_e32 v89, v87, v88
	v_sub_f32_e32 v88, v144, v223
	v_mul_f32_e32 v88, 0x3d800000, v88
	v_mul_f32_e32 v88, 0x3fb8aa3b, v88
	v_exp_f32_e32 v88, v88
	v_sub_f32_e32 v120, v175, v223
	v_mul_f32_e32 v120, 0x3d800000, v120
	v_mul_f32_e32 v120, 0x3fb8aa3b, v120
	v_add_f32_e32 v90, v88, v89
	v_sub_f32_e32 v89, v145, v223
	v_mul_f32_e32 v89, 0x3d800000, v89
	v_mul_f32_e32 v89, 0x3fb8aa3b, v89
	v_exp_f32_e32 v89, v89
	v_exp_f32_e32 v120, v120
	v_sub_f32_e32 v122, v177, v223
	v_mul_f32_e32 v122, 0x3d800000, v122
	v_add_f32_e32 v91, v89, v90
	v_sub_f32_e32 v90, v146, v223
	v_mul_f32_e32 v90, 0x3d800000, v90
	v_mul_f32_e32 v90, 0x3fb8aa3b, v90
	v_exp_f32_e32 v90, v90
	v_mul_f32_e32 v122, 0x3fb8aa3b, v122
	v_exp_f32_e32 v122, v122
	v_sub_f32_e32 v124, v179, v223
	v_add_f32_e32 v92, v90, v91
	v_sub_f32_e32 v91, v147, v223
	v_mul_f32_e32 v91, 0x3d800000, v91
	v_mul_f32_e32 v91, 0x3fb8aa3b, v91
	v_exp_f32_e32 v91, v91
	v_mul_f32_e32 v124, 0x3d800000, v124
	v_mul_f32_e32 v124, 0x3fb8aa3b, v124
	v_exp_f32_e32 v124, v124
	v_add_f32_e32 v93, v91, v92
	v_sub_f32_e32 v92, v148, v223
	v_mul_f32_e32 v92, 0x3d800000, v92
	v_mul_f32_e32 v92, 0x3fb8aa3b, v92
	v_exp_f32_e32 v92, v92
	v_sub_f32_e32 v126, v181, v223
	v_mul_f32_e32 v126, 0x3d800000, v126
	v_mul_f32_e32 v126, 0x3fb8aa3b, v126
	v_add_f32_e32 v94, v92, v93
	v_sub_f32_e32 v93, v149, v223
	v_mul_f32_e32 v93, 0x3d800000, v93
	v_mul_f32_e32 v93, 0x3fb8aa3b, v93
	v_exp_f32_e32 v93, v93
	v_exp_f32_e32 v126, v126
	v_sub_f32_e32 v68, v68, v223
	v_mul_f32_e32 v68, 0x3d800000, v68
	v_add_f32_e32 v94, v93, v94
	v_add_f32_e32 v94, v96, v94
	v_add_f32_e32 v94, v97, v94
	v_add_f32_e32 v94, v99, v94
	v_add_f32_e32 v94, v101, v94
	v_add_f32_e32 v94, v104, v94
	v_add_f32_e32 v94, v105, v94
	v_add_f32_e32 v94, v107, v94
	v_add_f32_e32 v94, v109, v94
	v_add_f32_e32 v94, v112, v94
	v_add_f32_e32 v95, v113, v94
	v_sub_f32_e32 v94, v160, v223
	v_mul_f32_e32 v94, 0x3d800000, v94
	v_mul_f32_e32 v94, 0x3fb8aa3b, v94
	v_exp_f32_e32 v94, v94
	v_sub_f32_e32 v69, v69, v223
	v_mul_f32_e32 v68, 0x3fb8aa3b, v68
	v_mul_f32_e32 v69, 0x3d800000, v69
	v_add_f32_e32 v98, v94, v95
	v_sub_f32_e32 v95, v161, v223
	v_mul_f32_e32 v95, 0x3d800000, v95
	v_mul_f32_e32 v95, 0x3fb8aa3b, v95
	v_exp_f32_e32 v95, v95
	v_sub_f32_e32 v70, v70, v223
	v_exp_f32_e32 v68, v68
	v_mul_f32_e32 v69, 0x3fb8aa3b, v69
	v_add_f32_e32 v100, v95, v98
	v_sub_f32_e32 v98, v162, v223
	v_mul_f32_e32 v98, 0x3d800000, v98
	v_mul_f32_e32 v98, 0x3fb8aa3b, v98
	v_exp_f32_e32 v98, v98
	v_mul_f32_e32 v70, 0x3d800000, v70
	v_sub_f32_e32 v71, v71, v223
	v_exp_f32_e32 v69, v69
	v_add_f32_e32 v102, v98, v100
	v_sub_f32_e32 v100, v163, v223
	v_mul_f32_e32 v100, 0x3d800000, v100
	v_mul_f32_e32 v100, 0x3fb8aa3b, v100
	v_exp_f32_e32 v100, v100
	v_mul_f32_e32 v70, 0x3fb8aa3b, v70
	v_mul_f32_e32 v71, 0x3d800000, v71
	v_exp_f32_e32 v70, v70
	v_add_f32_e32 v103, v100, v102
	v_sub_f32_e32 v102, v164, v223
	v_mul_f32_e32 v102, 0x3d800000, v102
	v_mul_f32_e32 v102, 0x3fb8aa3b, v102
	v_exp_f32_e32 v102, v102
	v_mul_f32_e32 v71, 0x3fb8aa3b, v71
	v_exp_f32_e32 v71, v71
	v_add_f32_e32 v106, v102, v103
	v_sub_f32_e32 v103, v165, v223
	v_mul_f32_e32 v103, 0x3d800000, v103
	v_mul_f32_e32 v103, 0x3fb8aa3b, v103
	v_exp_f32_e32 v103, v103
	s_nop 0
	v_add_f32_e32 v108, v103, v106
	v_sub_f32_e32 v106, v166, v223
	v_mul_f32_e32 v106, 0x3d800000, v106
	v_mul_f32_e32 v106, 0x3fb8aa3b, v106
	v_exp_f32_e32 v106, v106
	s_nop 0
	v_add_f32_e32 v110, v106, v108
	v_sub_f32_e32 v108, v167, v223
	v_mul_f32_e32 v108, 0x3d800000, v108
	v_mul_f32_e32 v108, 0x3fb8aa3b, v108
	v_exp_f32_e32 v108, v108
	s_nop 0
	v_add_f32_e32 v111, v108, v110
	v_sub_f32_e32 v110, v168, v223
	v_mul_f32_e32 v110, 0x3d800000, v110
	v_mul_f32_e32 v110, 0x3fb8aa3b, v110
	v_exp_f32_e32 v110, v110
	s_nop 0
	v_add_f32_e32 v114, v110, v111
	v_sub_f32_e32 v111, v169, v223
	v_mul_f32_e32 v111, 0x3d800000, v111
	v_mul_f32_e32 v111, 0x3fb8aa3b, v111
	v_exp_f32_e32 v111, v111
	s_nop 0
	v_add_f32_e32 v115, v111, v114
	v_sub_f32_e32 v114, v170, v223
	v_mul_f32_e32 v114, 0x3d800000, v114
	v_mul_f32_e32 v114, 0x3fb8aa3b, v114
	v_exp_f32_e32 v114, v114
	s_nop 0
	v_add_f32_e32 v115, v114, v115
	v_add_f32_e32 v117, v116, v115
	v_sub_f32_e32 v115, v172, v223
	v_mul_f32_e32 v115, 0x3d800000, v115
	v_mul_f32_e32 v115, 0x3fb8aa3b, v115
	v_exp_f32_e32 v115, v115
	s_nop 0
	v_add_f32_e32 v117, v115, v117
	v_add_f32_e32 v119, v118, v117
	v_sub_f32_e32 v117, v174, v223
	v_mul_f32_e32 v117, 0x3d800000, v117
	v_mul_f32_e32 v117, 0x3fb8aa3b, v117
	v_exp_f32_e32 v117, v117
	s_nop 0
	v_add_f32_e32 v119, v117, v119
	v_add_f32_e32 v121, v120, v119
	v_sub_f32_e32 v119, v176, v223
	v_mul_f32_e32 v119, 0x3d800000, v119
	v_mul_f32_e32 v119, 0x3fb8aa3b, v119
	v_exp_f32_e32 v119, v119
	s_nop 0
	v_add_f32_e32 v121, v119, v121
	v_add_f32_e32 v123, v122, v121
	v_sub_f32_e32 v121, v178, v223
	v_mul_f32_e32 v121, 0x3d800000, v121
	v_mul_f32_e32 v121, 0x3fb8aa3b, v121
	v_exp_f32_e32 v121, v121
	s_nop 0
	v_add_f32_e32 v123, v121, v123
	v_add_f32_e32 v125, v124, v123
	v_sub_f32_e32 v123, v180, v223
	v_mul_f32_e32 v123, 0x3d800000, v123
	v_mul_f32_e32 v123, 0x3fb8aa3b, v123
	v_exp_f32_e32 v123, v123
	s_nop 0
	v_add_f32_e32 v125, v123, v125
	v_add_f32_e32 v127, v126, v125
	v_sub_f32_e32 v125, v182, v223
	v_mul_f32_e32 v125, 0x3d800000, v125
	v_mul_f32_e32 v125, 0x3fb8aa3b, v125
	v_exp_f32_e32 v125, v125
	s_nop 0
	v_add_f32_e32 v128, v125, v127
	v_sub_f32_e32 v127, v183, v223
	v_mul_f32_e32 v127, 0x3d800000, v127
	v_mul_f32_e32 v127, 0x3fb8aa3b, v127
	v_exp_f32_e32 v127, v127
	s_nop 0
	v_add_f32_e32 v128, v127, v128
	v_add_f32_e32 v128, v68, v128
	v_add_f32_e32 v128, v69, v128
	v_add_f32_e32 v128, v70, v128
	v_add_f32_e32 v128, v71, v128
	ds_bpermute_b32 v129, v198, v128
	s_waitcnt lgkmcnt(0)
	v_add_f32_e32 v152, v128, v129
	v_max_f32_e32 v128, v1, v1
	v_max_f32_e32 v129, v0, v0
	v_max_f32_e32 v128, v129, v128
	v_max3_f32 v128, v128, v2, v3
	v_max3_f32 v128, v128, v4, v5
	v_max3_f32 v128, v128, v6, v7
	v_max3_f32 v128, v128, v8, v9
	v_max3_f32 v128, v128, v10, v11
	v_max3_f32 v128, v128, v12, v13
	v_max3_f32 v128, v128, v14, v15
	v_max3_f32 v128, v128, v16, v17
	v_max3_f32 v128, v128, v18, v19
	v_max3_f32 v128, v128, v20, v21
	v_max3_f32 v128, v128, v22, v23
	v_max3_f32 v128, v128, v24, v25
	v_max3_f32 v128, v128, v26, v27
	v_max3_f32 v128, v128, v28, v29
	v_max3_f32 v128, v128, v30, v31
	v_max3_f32 v128, v128, v32, v33
	v_max3_f32 v128, v128, v34, v35
	v_max3_f32 v128, v128, v36, v37
	v_max3_f32 v128, v128, v38, v39
	v_max3_f32 v128, v128, v40, v41
	v_max3_f32 v128, v128, v42, v43
	v_max3_f32 v128, v128, v44, v45
	v_max3_f32 v128, v128, v46, v47
	v_max3_f32 v128, v128, v48, v49
	v_max3_f32 v128, v128, v50, v51
	v_max3_f32 v128, v128, v52, v53
	v_max3_f32 v128, v128, v54, v55
	v_max3_f32 v128, v128, v56, v57
	v_max3_f32 v128, v128, v58, v59
	v_max3_f32 v128, v128, v60, v61
	v_max3_f32 v128, v128, v62, v63
	ds_bpermute_b32 v129, v198, v128
	ds_bpermute_b32 v153, v199, v152
	s_waitcnt lgkmcnt(1)
	v_max_f32_e32 v129, v129, v129
	v_max_f32_e32 v128, v128, v129
	ds_bpermute_b32 v129, v199, v128
	s_waitcnt lgkmcnt(0)
	v_max_f32_e32 v129, v129, v129
	v_max_f32_e32 v154, v128, v129
	v_sub_f32_e32 v1, v1, v154
	v_mul_f32_e32 v1, 0x3d800000, v1
	v_mul_f32_e32 v1, 0x3fb8aa3b, v1
	v_exp_f32_e32 v130, v1
	v_sub_f32_e32 v1, v2, v154
	v_mul_f32_e32 v1, 0x3d800000, v1
	v_mul_f32_e32 v1, 0x3fb8aa3b, v1
	v_exp_f32_e32 v129, v1
	v_sub_f32_e32 v1, v3, v154
	v_mul_f32_e32 v1, 0x3d800000, v1
	v_mul_f32_e32 v1, 0x3fb8aa3b, v1
	v_exp_f32_e32 v131, v1
	v_sub_f32_e32 v1, v4, v154
	v_mul_f32_e32 v1, 0x3d800000, v1
	v_mul_f32_e32 v1, 0x3fb8aa3b, v1
	v_exp_f32_e32 v132, v1
	v_sub_f32_e32 v1, v5, v154
	v_mul_f32_e32 v1, 0x3d800000, v1
	v_mul_f32_e32 v1, 0x3fb8aa3b, v1
	v_exp_f32_e32 v133, v1
	v_sub_f32_e32 v1, v6, v154
	v_mul_f32_e32 v1, 0x3d800000, v1
	v_mul_f32_e32 v1, 0x3fb8aa3b, v1
	v_exp_f32_e32 v134, v1
	v_sub_f32_e32 v1, v7, v154
	v_mul_f32_e32 v1, 0x3d800000, v1
	v_mul_f32_e32 v1, 0x3fb8aa3b, v1
	v_exp_f32_e32 v135, v1
	v_sub_f32_e32 v1, v8, v154
	v_mul_f32_e32 v1, 0x3d800000, v1
	v_mul_f32_e32 v1, 0x3fb8aa3b, v1
	v_exp_f32_e32 v136, v1
	v_sub_f32_e32 v1, v9, v154
	v_mul_f32_e32 v1, 0x3d800000, v1
	v_mul_f32_e32 v1, 0x3fb8aa3b, v1
	v_exp_f32_e32 v138, v1
	v_sub_f32_e32 v1, v10, v154
	v_mul_f32_e32 v1, 0x3d800000, v1
	v_mul_f32_e32 v1, 0x3fb8aa3b, v1
	v_exp_f32_e32 v137, v1
	v_sub_f32_e32 v1, v11, v154
	v_mul_f32_e32 v1, 0x3d800000, v1
	v_mul_f32_e32 v1, 0x3fb8aa3b, v1
	v_exp_f32_e32 v139, v1
	v_sub_f32_e32 v1, v12, v154
	v_mul_f32_e32 v1, 0x3d800000, v1
	v_mul_f32_e32 v1, 0x3fb8aa3b, v1
	v_exp_f32_e32 v140, v1
	v_sub_f32_e32 v1, v13, v154
	v_mul_f32_e32 v1, 0x3d800000, v1
	v_mul_f32_e32 v1, 0x3fb8aa3b, v1
	v_exp_f32_e32 v141, v1
	v_sub_f32_e32 v1, v14, v154
	v_mul_f32_e32 v1, 0x3d800000, v1
	v_mul_f32_e32 v1, 0x3fb8aa3b, v1
	v_exp_f32_e32 v142, v1
	v_sub_f32_e32 v1, v15, v154
	v_mul_f32_e32 v1, 0x3d800000, v1
	v_mul_f32_e32 v1, 0x3fb8aa3b, v1
	v_exp_f32_e32 v143, v1
	v_sub_f32_e32 v1, v16, v154
	v_mul_f32_e32 v1, 0x3d800000, v1
	v_mul_f32_e32 v1, 0x3fb8aa3b, v1
	v_exp_f32_e32 v144, v1
	v_sub_f32_e32 v1, v17, v154
	v_mul_f32_e32 v1, 0x3d800000, v1
	v_mul_f32_e32 v1, 0x3fb8aa3b, v1
	v_exp_f32_e32 v146, v1
	v_sub_f32_e32 v1, v18, v154
	v_mul_f32_e32 v1, 0x3d800000, v1
	v_mul_f32_e32 v1, 0x3fb8aa3b, v1
	v_exp_f32_e32 v145, v1
	v_sub_f32_e32 v1, v19, v154
	v_mul_f32_e32 v1, 0x3d800000, v1
	v_mul_f32_e32 v1, 0x3fb8aa3b, v1
	v_exp_f32_e32 v147, v1
	v_sub_f32_e32 v1, v20, v154
	v_mul_f32_e32 v1, 0x3d800000, v1
	v_mul_f32_e32 v1, 0x3fb8aa3b, v1
	v_exp_f32_e32 v148, v1
	v_sub_f32_e32 v1, v21, v154
	v_mul_f32_e32 v1, 0x3d800000, v1
	v_mul_f32_e32 v1, 0x3fb8aa3b, v1
	v_exp_f32_e32 v149, v1
	v_sub_f32_e32 v1, v22, v154
	v_mul_f32_e32 v1, 0x3d800000, v1
	v_mul_f32_e32 v1, 0x3fb8aa3b, v1
	v_exp_f32_e32 v150, v1
	v_sub_f32_e32 v1, v23, v154
	v_mul_f32_e32 v1, 0x3d800000, v1
	v_mul_f32_e32 v1, 0x3fb8aa3b, v1
	v_exp_f32_e32 v151, v1
	v_sub_f32_e32 v1, v24, v154
	v_mul_f32_e32 v1, 0x3d800000, v1
	v_mul_f32_e32 v1, 0x3fb8aa3b, v1
	v_exp_f32_e32 v156, v1
	v_sub_f32_e32 v1, v25, v154
	v_mul_f32_e32 v1, 0x3d800000, v1
	v_mul_f32_e32 v1, 0x3fb8aa3b, v1
	v_exp_f32_e32 v158, v1
	v_sub_f32_e32 v1, v26, v154
	v_mul_f32_e32 v1, 0x3d800000, v1
	v_mul_f32_e32 v1, 0x3fb8aa3b, v1
	v_exp_f32_e32 v157, v1
	v_sub_f32_e32 v1, v27, v154
	v_mul_f32_e32 v1, 0x3d800000, v1
	v_mul_f32_e32 v1, 0x3fb8aa3b, v1
	v_exp_f32_e32 v27, v1
	v_sub_f32_e32 v1, v28, v154
	v_mul_f32_e32 v1, 0x3d800000, v1
	v_mul_f32_e32 v1, 0x3fb8aa3b, v1
	v_exp_f32_e32 v28, v1
	v_sub_f32_e32 v1, v29, v154
	v_mul_f32_e32 v1, 0x3d800000, v1
	v_mul_f32_e32 v1, 0x3fb8aa3b, v1
	v_exp_f32_e32 v29, v1
	v_sub_f32_e32 v1, v30, v154
	v_mul_f32_e32 v1, 0x3d800000, v1
	v_mul_f32_e32 v1, 0x3fb8aa3b, v1
	v_exp_f32_e32 v30, v1
	v_sub_f32_e32 v1, v31, v154
	v_mul_f32_e32 v1, 0x3d800000, v1
	v_mul_f32_e32 v1, 0x3fb8aa3b, v1
	v_exp_f32_e32 v31, v1
	v_sub_f32_e32 v1, v32, v154
	v_mul_f32_e32 v1, 0x3d800000, v1
	v_mul_f32_e32 v1, 0x3fb8aa3b, v1
	v_exp_f32_e32 v32, v1
	v_sub_f32_e32 v1, v33, v154
	v_mul_f32_e32 v1, 0x3d800000, v1
	v_mul_f32_e32 v1, 0x3fb8aa3b, v1
	v_exp_f32_e32 v159, v1
	v_sub_f32_e32 v1, v34, v154
	v_mul_f32_e32 v1, 0x3d800000, v1
	v_mul_f32_e32 v1, 0x3fb8aa3b, v1
	v_exp_f32_e32 v33, v1
	v_sub_f32_e32 v1, v35, v154
	v_mul_f32_e32 v1, 0x3d800000, v1
	v_mul_f32_e32 v1, 0x3fb8aa3b, v1
	v_exp_f32_e32 v34, v1
	v_sub_f32_e32 v1, v36, v154
	v_mul_f32_e32 v1, 0x3d800000, v1
	v_mul_f32_e32 v1, 0x3fb8aa3b, v1
	v_exp_f32_e32 v35, v1
	v_sub_f32_e32 v1, v37, v154
	v_mul_f32_e32 v1, 0x3d800000, v1
	v_mul_f32_e32 v1, 0x3fb8aa3b, v1
	v_exp_f32_e32 v36, v1
	v_sub_f32_e32 v1, v38, v154
	v_mul_f32_e32 v1, 0x3d800000, v1
	v_mul_f32_e32 v1, 0x3fb8aa3b, v1
	v_exp_f32_e32 v37, v1
	v_sub_f32_e32 v1, v39, v154
	v_mul_f32_e32 v1, 0x3d800000, v1
	v_mul_f32_e32 v1, 0x3fb8aa3b, v1
	v_exp_f32_e32 v38, v1
	v_sub_f32_e32 v1, v40, v154
	v_mul_f32_e32 v1, 0x3d800000, v1
	v_mul_f32_e32 v1, 0x3fb8aa3b, v1
	v_exp_f32_e32 v39, v1
	v_sub_f32_e32 v1, v41, v154
	v_mul_f32_e32 v1, 0x3d800000, v1
	v_mul_f32_e32 v1, 0x3fb8aa3b, v1
	v_sub_f32_e32 v0, v0, v154
	v_exp_f32_e32 v41, v1
	v_sub_f32_e32 v1, v42, v154
	v_mul_f32_e32 v0, 0x3d800000, v0
	v_mul_f32_e32 v1, 0x3d800000, v1
	v_mul_f32_e32 v0, 0x3fb8aa3b, v0
	v_mul_f32_e32 v1, 0x3fb8aa3b, v1
	v_exp_f32_e32 v128, v0
	v_exp_f32_e32 v40, v1
	v_sub_f32_e32 v1, v43, v154
	v_mul_f32_e32 v1, 0x3d800000, v1
	v_mul_f32_e32 v1, 0x3fb8aa3b, v1
	v_exp_f32_e32 v42, v1
	v_sub_f32_e32 v1, v44, v154
	v_add_f32_e32 v0, 0, v128
	v_mul_f32_e32 v1, 0x3d800000, v1
	v_add_f32_e32 v0, v130, v0
	v_mul_f32_e32 v1, 0x3fb8aa3b, v1
	v_add_f32_e32 v0, v129, v0
	v_exp_f32_e32 v43, v1
	v_sub_f32_e32 v1, v45, v154
	v_add_f32_e32 v0, v131, v0
	v_mul_f32_e32 v1, 0x3d800000, v1
	v_add_f32_e32 v0, v132, v0
	v_mul_f32_e32 v1, 0x3fb8aa3b, v1
	v_add_f32_e32 v0, v133, v0
	v_exp_f32_e32 v160, v1
	v_sub_f32_e32 v1, v46, v154
	v_add_f32_e32 v0, v134, v0
	v_mul_f32_e32 v1, 0x3d800000, v1
	v_add_f32_e32 v0, v135, v0
	v_mul_f32_e32 v1, 0x3fb8aa3b, v1
	v_add_f32_e32 v0, v136, v0
	v_exp_f32_e32 v161, v1
	v_sub_f32_e32 v1, v47, v154
	v_add_f32_e32 v0, v138, v0
	v_mul_f32_e32 v1, 0x3d800000, v1
	v_add_f32_e32 v0, v137, v0
	v_mul_f32_e32 v1, 0x3fb8aa3b, v1
	v_add_f32_e32 v0, v139, v0
	v_exp_f32_e32 v162, v1
	v_sub_f32_e32 v1, v48, v154
	v_add_f32_e32 v0, v140, v0
	v_mul_f32_e32 v1, 0x3d800000, v1
	v_add_f32_e32 v0, v141, v0
	v_mul_f32_e32 v1, 0x3fb8aa3b, v1
	v_add_f32_e32 v0, v142, v0
	v_exp_f32_e32 v163, v1
	v_sub_f32_e32 v1, v49, v154
	v_add_f32_e32 v0, v143, v0
	v_mul_f32_e32 v1, 0x3d800000, v1
	v_add_f32_e32 v0, v144, v0
	v_mul_f32_e32 v1, 0x3fb8aa3b, v1
	v_add_f32_e32 v0, v146, v0
	v_exp_f32_e32 v165, v1
	v_sub_f32_e32 v1, v50, v154
	v_add_f32_e32 v0, v145, v0
	v_mul_f32_e32 v1, 0x3d800000, v1
	v_add_f32_e32 v0, v147, v0
	v_mul_f32_e32 v1, 0x3fb8aa3b, v1
	v_add_f32_e32 v0, v148, v0
	v_exp_f32_e32 v164, v1
	v_sub_f32_e32 v1, v51, v154
	v_add_f32_e32 v0, v149, v0
	v_mul_f32_e32 v1, 0x3d800000, v1
	v_add_f32_e32 v0, v150, v0
	v_mul_f32_e32 v1, 0x3fb8aa3b, v1
	v_add_f32_e32 v0, v151, v0
	v_exp_f32_e32 v166, v1
	v_sub_f32_e32 v1, v52, v154
	v_add_f32_e32 v0, v156, v0
	v_mul_f32_e32 v1, 0x3d800000, v1
	v_add_f32_e32 v0, v158, v0
	v_mul_f32_e32 v1, 0x3fb8aa3b, v1
	v_add_f32_e32 v0, v157, v0
	v_exp_f32_e32 v167, v1
	v_sub_f32_e32 v1, v53, v154
	v_add_f32_e32 v0, v27, v0
	v_mul_f32_e32 v1, 0x3d800000, v1
	v_add_f32_e32 v0, v28, v0
	v_mul_f32_e32 v1, 0x3fb8aa3b, v1
	v_add_f32_e32 v0, v29, v0
	v_exp_f32_e32 v168, v1
	v_sub_f32_e32 v1, v54, v154
	v_add_f32_e32 v0, v30, v0
	v_mul_f32_e32 v1, 0x3d800000, v1
	v_add_f32_e32 v0, v31, v0
	v_mul_f32_e32 v1, 0x3fb8aa3b, v1
	v_add_f32_e32 v0, v32, v0
	v_exp_f32_e32 v169, v1
	v_sub_f32_e32 v1, v55, v154
	v_add_f32_e32 v0, v159, v0
	v_mul_f32_e32 v1, 0x3d800000, v1
	v_add_f32_e32 v0, v33, v0
	v_mul_f32_e32 v1, 0x3fb8aa3b, v1
	v_add_f32_e32 v0, v34, v0
	v_exp_f32_e32 v170, v1
	v_sub_f32_e32 v1, v56, v154
	v_add_f32_e32 v0, v35, v0
	v_mul_f32_e32 v1, 0x3d800000, v1
	v_add_f32_e32 v0, v36, v0
	v_mul_f32_e32 v1, 0x3fb8aa3b, v1
	v_add_f32_e32 v0, v37, v0
	v_exp_f32_e32 v171, v1
	v_sub_f32_e32 v1, v57, v154
	v_add_f32_e32 v0, v38, v0
	v_mul_f32_e32 v1, 0x3d800000, v1
	v_add_f32_e32 v0, v39, v0
	v_mul_f32_e32 v1, 0x3fb8aa3b, v1
	v_add_f32_e32 v0, v41, v0
	v_exp_f32_e32 v172, v1
	v_sub_f32_e32 v1, v58, v154
	v_add_f32_e32 v0, v40, v0
	v_mul_f32_e32 v1, 0x3d800000, v1
	v_add_f32_e32 v0, v42, v0
	v_mul_f32_e32 v1, 0x3fb8aa3b, v1
	v_add_f32_e32 v0, v43, v0
	v_exp_f32_e32 v173, v1
	v_sub_f32_e32 v1, v59, v154
	v_add_f32_e32 v0, v160, v0
	v_mul_f32_e32 v1, 0x3d800000, v1
	v_add_f32_e32 v0, v161, v0
	v_mul_f32_e32 v1, 0x3fb8aa3b, v1
	v_add_f32_e32 v0, v162, v0
	v_exp_f32_e32 v174, v1
	v_sub_f32_e32 v1, v60, v154
	v_add_f32_e32 v0, v163, v0
	v_mul_f32_e32 v1, 0x3d800000, v1
	v_add_f32_e32 v0, v165, v0
	v_mul_f32_e32 v1, 0x3fb8aa3b, v1
	v_add_f32_e32 v0, v164, v0
	v_exp_f32_e32 v175, v1
	v_sub_f32_e32 v1, v61, v154
	v_add_f32_e32 v0, v166, v0
	v_mul_f32_e32 v1, 0x3d800000, v1
	v_add_f32_e32 v0, v167, v0
	v_mul_f32_e32 v1, 0x3fb8aa3b, v1
	v_add_f32_e32 v0, v168, v0
	v_exp_f32_e32 v176, v1
	v_sub_f32_e32 v1, v62, v154
	v_add_f32_e32 v0, v169, v0
	v_mul_f32_e32 v1, 0x3d800000, v1
	v_add_f32_e32 v0, v170, v0
	v_mul_f32_e32 v1, 0x3fb8aa3b, v1
	v_add_f32_e32 v0, v171, v0
	v_exp_f32_e32 v177, v1
	v_sub_f32_e32 v1, v63, v154
	v_add_f32_e32 v0, v172, v0
	v_mul_f32_e32 v1, 0x3d800000, v1
	v_add_f32_e32 v0, v173, v0
	v_mul_f32_e32 v1, 0x3fb8aa3b, v1
	v_add_f32_e32 v0, v174, v0
	v_exp_f32_e32 v178, v1
	v_add_f32_e32 v0, v175, v0
	v_add_f32_e32 v0, v176, v0
	v_add_f32_e32 v0, v177, v0
	v_add_f32_e32 v0, v178, v0
	ds_bpermute_b32 v1, v198, v0
	s_waitcnt lgkmcnt(0)
	v_add_f32_e32 v154, v0, v1
	ds_bpermute_b32 v155, v199, v154
	global_load_dwordx4 v[0:3], v252, s[14:15]
	s_add_u32 s14, s14, 0x10000
	s_addc_u32 s15, s15, 0
	global_load_dwordx4 v[4:7], v252, s[14:15]
	s_add_u32 s14, s14, 0x10000
	s_addc_u32 s15, s15, 0
	global_load_dwordx4 v[8:11], v252, s[14:15]
	s_add_u32 s14, s14, 0x10000
	s_addc_u32 s15, s15, 0
	global_load_dwordx4 v[12:15], v252, s[14:15]
	s_add_u32 s14, s14, 0x10000
	s_addc_u32 s15, s15, 0
	global_load_dwordx4 v[16:19], v252, s[14:15]
	s_add_u32 s14, s14, 0x10000
	s_addc_u32 s15, s15, 0
	global_load_dwordx4 v[20:23], v252, s[14:15]
	s_add_u32 s14, s14, 0x10000
	s_addc_u32 s15, s15, 0
	global_load_dwordx4 v[44:47], v252, s[14:15]
	s_add_u32 s14, s14, 0x10000
	s_addc_u32 s15, s15, 0
	global_load_dwordx4 v[48:51], v252, s[14:15]
	s_add_u32 s14, s14, 0x10000
	s_addc_u32 s15, s15, 0
	global_load_dwordx4 v[52:55], v252, s[14:15]
	s_add_u32 s14, s14, 0x10000
	s_addc_u32 s15, s15, 0
	s_waitcnt vmcnt(15)
	ds_write_b128 v196, v[224:227]
	s_waitcnt vmcnt(14)
	ds_write_b128 v196, v[228:231] offset:8448
	s_waitcnt vmcnt(13)
	ds_write_b128 v196, v[232:235] offset:16896
	s_waitcnt vmcnt(12)
	ds_write_b128 v196, v[236:239] offset:25344
	s_waitcnt vmcnt(11)
	ds_write_b128 v196, v[240:243] offset:33792
	s_waitcnt vmcnt(10)
	ds_write_b128 v196, v[244:247] offset:42240
	s_waitcnt vmcnt(9)
	ds_write_b128 v196, v[248:251] offset:50688
	s_waitcnt vmcnt(8)
	ds_write_b128 v196, v[0:3] offset:59136
	s_waitcnt vmcnt(7)
	ds_write_b128 v253, v[4:7]
	s_waitcnt vmcnt(6)
	ds_write_b128 v253, v[8:11] offset:8448
	s_waitcnt vmcnt(5)
	ds_write_b128 v253, v[12:15] offset:16896
	s_waitcnt vmcnt(4)
	ds_write_b128 v253, v[16:19] offset:25344
	s_waitcnt vmcnt(3)
	ds_write_b128 v253, v[20:23] offset:33792
	s_waitcnt vmcnt(2)
	ds_write_b128 v253, v[44:47] offset:42240
	s_waitcnt vmcnt(1)
	ds_write_b128 v253, v[48:51] offset:50688
	s_waitcnt vmcnt(0)
	ds_write_b128 v253, v[52:55] offset:59136
	s_waitcnt lgkmcnt(0)
	s_barrier
	ds_read2_b64 v[44:47], v211 offset1:4
	ds_read2_b64 v[48:51], v211 offset0:8 offset1:12
	v_cvt_pk_bf16_f32 v16, v64, v65
	v_cvt_pk_bf16_f32 v17, v66, v67
	v_cvt_pk_bf16_f32 v18, v72, v73
	v_cvt_pk_bf16_f32 v19, v74, v75
	v_cvt_pk_bf16_f32 v60, v128, v130
	v_cvt_pk_bf16_f32 v61, v129, v131
	v_cvt_pk_bf16_f32 v62, v132, v133
	v_cvt_pk_bf16_f32 v63, v134, v135
	ds_read2_b64 v[64:67], v211 offset0:16 offset1:20
	s_waitcnt lgkmcnt(2)
	v_mfma_f32_16x16x32_bf16 v[52:55], v[44:47], v[16:19], 0
	v_cvt_pk_bf16_f32 v12, v76, v77
	v_cvt_pk_bf16_f32 v13, v78, v79
	v_cvt_pk_bf16_f32 v14, v80, v81
	v_mfma_f32_16x16x32_bf16 v[44:47], v[44:47], v[60:63], 0
	v_cvt_pk_bf16_f32 v15, v82, v83
	v_cvt_pk_bf16_f32 v56, v136, v138
	v_cvt_pk_bf16_f32 v57, v137, v139
	v_cvt_pk_bf16_f32 v58, v140, v141
	v_cvt_pk_bf16_f32 v59, v142, v143
	ds_read2_b64 v[76:79], v211 offset0:24 offset1:28
	s_waitcnt lgkmcnt(2)
	v_mfma_f32_16x16x32_bf16 v[72:75], v[48:51], v[12:15], v[52:55]
	v_cvt_pk_bf16_f32 v8, v84, v85
	v_cvt_pk_bf16_f32 v9, v86, v87
	v_cvt_pk_bf16_f32 v10, v88, v89
	v_mfma_f32_16x16x32_bf16 v[44:47], v[48:51], v[56:59], v[44:47]
	v_cvt_pk_bf16_f32 v11, v90, v91
	v_cvt_pk_bf16_f32 v52, v144, v146
	v_cvt_pk_bf16_f32 v53, v145, v147
	v_cvt_pk_bf16_f32 v54, v148, v149
	v_cvt_pk_bf16_f32 v55, v150, v151
	s_waitcnt lgkmcnt(1)
	v_mfma_f32_16x16x32_bf16 v[72:75], v[64:67], v[8:11], v[72:75]
	v_cvt_pk_bf16_f32 v4, v92, v93
	v_cvt_pk_bf16_f32 v5, v96, v97
	v_cvt_pk_bf16_f32 v6, v99, v101
	v_mfma_f32_16x16x32_bf16 v[44:47], v[64:67], v[52:55], v[44:47]
	ds_read2_b64 v[64:67], v211 offset0:32 offset1:36
	v_cvt_pk_bf16_f32 v7, v104, v105
	v_cvt_pk_bf16_f32 v48, v156, v158
	v_cvt_pk_bf16_f32 v49, v157, v27
	v_cvt_pk_bf16_f32 v50, v28, v29
	v_cvt_pk_bf16_f32 v51, v30, v31
	s_waitcnt lgkmcnt(1)
	v_mfma_f32_16x16x32_bf16 v[72:75], v[76:79], v[4:7], v[72:75]
	v_cvt_pk_bf16_f32 v0, v107, v109
	v_cvt_pk_bf16_f32 v1, v112, v113
	v_cvt_pk_bf16_f32 v2, v94, v95
	v_mfma_f32_16x16x32_bf16 v[28:31], v[76:79], v[48:51], v[44:47]
	ds_read2_b64 v[76:79], v211 offset0:40 offset1:44
	v_cvt_pk_bf16_f32 v3, v98, v100
	v_cvt_pk_bf16_f32 v20, v102, v103
	v_cvt_pk_bf16_f32 v44, v32, v159
	v_cvt_pk_bf16_f32 v45, v33, v34
	v_cvt_pk_bf16_f32 v46, v35, v36
	v_cvt_pk_bf16_f32 v47, v37, v38
	s_waitcnt lgkmcnt(1)
	v_mfma_f32_16x16x32_bf16 v[72:75], v[64:67], v[0:3], v[72:75]
	v_cvt_pk_bf16_f32 v21, v106, v108
	v_cvt_pk_bf16_f32 v22, v110, v111
	v_cvt_pk_bf16_f32 v23, v114, v116
	v_mfma_f32_16x16x32_bf16 v[30:33], v[64:67], v[44:47], v[28:31]
	ds_read2_b64 v[64:67], v211 offset0:48 offset1:52
	v_cvt_pk_bf16_f32 v36, v39, v41
	v_cvt_pk_bf16_f32 v37, v40, v42
	v_cvt_pk_bf16_f32 v38, v43, v160
	v_cvt_pk_bf16_f32 v39, v161, v162
	s_waitcnt lgkmcnt(1)
	v_mfma_f32_16x16x32_bf16 v[72:75], v[76:79], v[20:23], v[72:75]
	v_cvt_pk_bf16_f32 v24, v115, v118
	v_cvt_pk_bf16_f32 v25, v117, v120
	v_cvt_pk_bf16_f32 v26, v119, v122
	v_mfma_f32_16x16x32_bf16 v[40:43], v[76:79], v[36:39], v[30:33]
	ds_read2_b64 v[76:79], v211 offset0:56 offset1:60
	v_cvt_pk_bf16_f32 v27, v121, v124
	v_cvt_pk_bf16_f32 v28, v123, v126
	v_cvt_pk_bf16_f32 v29, v125, v127
	s_waitcnt lgkmcnt(1)
	v_mfma_f32_16x16x32_bf16 v[72:75], v[64:67], v[24:27], v[72:75]
	v_cvt_pk_bf16_f32 v30, v68, v69
	v_cvt_pk_bf16_f32 v31, v70, v71
	v_add_u32_e32 v84, 0x2000, v211
	v_cvt_pk_bf16_f32 v32, v163, v165
	s_waitcnt lgkmcnt(0)
	v_mfma_f32_16x16x32_bf16 v[68:71], v[76:79], v[28:31], v[72:75]
	v_cvt_pk_bf16_f32 v33, v164, v166
	v_cvt_pk_bf16_f32 v34, v167, v168
	v_cvt_pk_bf16_f32 v35, v169, v170
	ds_read2_b64 v[72:75], v84 offset0:32 offset1:36
	ds_read2_b64 v[80:83], v84 offset0:40 offset1:44
	v_mfma_f32_16x16x32_bf16 v[64:67], v[64:67], v[32:35], v[40:43]
	v_add_u32_e32 v92, 0x4000, v211
	ds_read2_b64 v[88:91], v92 offset0:72 offset1:76
	v_add_u32_e32 v100, v200, v201
	v_cvt_pk_bf16_f32 v40, v171, v172
	v_cvt_pk_bf16_f32 v41, v173, v174
	v_cvt_pk_bf16_f32 v42, v175, v176
	v_cvt_pk_bf16_f32 v43, v177, v178
	ds_read2_b64 v[96:99], v100 offset0:8 offset1:12
	v_add_u32_e32 v108, 0x8000, v211
	v_mfma_f32_16x16x32_bf16 v[64:67], v[76:79], v[40:43], v[64:67]
	ds_read2_b64 v[104:107], v108 offset0:136 offset1:140
	v_add_u32_e32 v116, 0xa000, v211
	ds_read2_b64 v[112:115], v116 offset0:168 offset1:172
	s_waitcnt lgkmcnt(5)
	v_mfma_f32_16x16x32_bf16 v[76:79], v[72:75], v[16:19], 0
	v_add_u32_e32 v124, 0xc000, v211
	ds_read2_b64 v[120:123], v124 offset0:200 offset1:204
	v_add_u32_e32 v132, v200, v202
	v_mfma_f32_16x16x32_bf16 v[72:75], v[72:75], v[60:63], 0
	ds_read2_b64 v[128:131], v132 offset0:8 offset1:12
	v_add_u32_e32 v140, v200, v203
	ds_read2_b64 v[136:139], v140 offset0:8 offset1:12
	s_waitcnt lgkmcnt(7)
	v_mfma_f32_16x16x32_bf16 v[76:79], v[80:83], v[12:15], v[76:79]
	v_add_u32_e32 v148, v200, v204
	ds_read2_b64 v[144:147], v148 offset0:8 offset1:12
	v_add_u32_e32 v160, v200, v205
	v_mfma_f32_16x16x32_bf16 v[72:75], v[80:83], v[56:59], v[72:75]
	ds_read2_b64 v[80:83], v84 offset0:48 offset1:52
	ds_read2_b64 v[156:159], v160 offset0:8 offset1:12
	v_add_u32_e32 v172, v200, v206
	s_waitcnt lgkmcnt(1)
	v_mfma_f32_16x16x32_bf16 v[76:79], v[80:83], v[8:11], v[76:79]
	ds_read2_b64 v[164:167], v172 offset0:8 offset1:12
	s_add_i32 s9, s9, s33
	s_cmpk_gt_i32 s9, 0x1ff
	v_mfma_f32_16x16x32_bf16 v[72:75], v[80:83], v[52:55], v[72:75]
	ds_read2_b64 v[80:83], v84 offset0:56 offset1:60
	s_waitcnt lgkmcnt(0)
	v_mfma_f32_16x16x32_bf16 v[76:79], v[80:83], v[4:7], v[76:79]
	v_mfma_f32_16x16x32_bf16 v[72:75], v[80:83], v[48:51], v[72:75]
	ds_read2_b64 v[80:83], v84 offset0:64 offset1:68
	s_waitcnt lgkmcnt(0)
	v_mfma_f32_16x16x32_bf16 v[76:79], v[80:83], v[0:3], v[76:79]
	v_mfma_f32_16x16x32_bf16 v[72:75], v[80:83], v[44:47], v[72:75]
	ds_read2_b64 v[80:83], v84 offset0:72 offset1:76
	s_waitcnt lgkmcnt(0)
	v_mfma_f32_16x16x32_bf16 v[76:79], v[80:83], v[20:23], v[76:79]
	v_mfma_f32_16x16x32_bf16 v[72:75], v[80:83], v[36:39], v[72:75]
	ds_read2_b64 v[80:83], v84 offset0:80 offset1:84
	s_waitcnt lgkmcnt(0)
	v_mfma_f32_16x16x32_bf16 v[76:79], v[80:83], v[24:27], v[76:79]
	v_mfma_f32_16x16x32_bf16 v[72:75], v[80:83], v[32:35], v[72:75]
	ds_read2_b64 v[80:83], v84 offset0:88 offset1:92
	s_waitcnt lgkmcnt(0)
	v_mfma_f32_16x16x32_bf16 v[76:79], v[80:83], v[28:31], v[76:79]
	v_mfma_f32_16x16x32_bf16 v[72:75], v[80:83], v[40:43], v[72:75]
	ds_read2_b64 v[80:83], v92 offset0:64 offset1:68
	s_waitcnt lgkmcnt(0)
	v_mfma_f32_16x16x32_bf16 v[84:87], v[80:83], v[16:19], 0
	v_mfma_f32_16x16x32_bf16 v[80:83], v[80:83], v[60:63], 0
	v_mfma_f32_16x16x32_bf16 v[84:87], v[88:91], v[12:15], v[84:87]
	v_mfma_f32_16x16x32_bf16 v[80:83], v[88:91], v[56:59], v[80:83]
	ds_read2_b64 v[88:91], v92 offset0:80 offset1:84
	s_waitcnt lgkmcnt(0)
	v_mfma_f32_16x16x32_bf16 v[84:87], v[88:91], v[8:11], v[84:87]
	v_mfma_f32_16x16x32_bf16 v[80:83], v[88:91], v[52:55], v[80:83]
	ds_read2_b64 v[88:91], v92 offset0:88 offset1:92
	s_waitcnt lgkmcnt(0)
	v_mfma_f32_16x16x32_bf16 v[84:87], v[88:91], v[4:7], v[84:87]
	v_mfma_f32_16x16x32_bf16 v[80:83], v[88:91], v[48:51], v[80:83]
	ds_read2_b64 v[88:91], v92 offset0:96 offset1:100
	s_waitcnt lgkmcnt(0)
	v_mfma_f32_16x16x32_bf16 v[84:87], v[88:91], v[0:3], v[84:87]
	v_mfma_f32_16x16x32_bf16 v[80:83], v[88:91], v[44:47], v[80:83]
	ds_read2_b64 v[88:91], v92 offset0:104 offset1:108
	s_waitcnt lgkmcnt(0)
	v_mfma_f32_16x16x32_bf16 v[84:87], v[88:91], v[20:23], v[84:87]
	v_mfma_f32_16x16x32_bf16 v[80:83], v[88:91], v[36:39], v[80:83]
	ds_read2_b64 v[88:91], v92 offset0:112 offset1:116
	s_waitcnt lgkmcnt(0)
	v_mfma_f32_16x16x32_bf16 v[84:87], v[88:91], v[24:27], v[84:87]
	v_mfma_f32_16x16x32_bf16 v[80:83], v[88:91], v[32:35], v[80:83]
	ds_read2_b64 v[88:91], v92 offset0:120 offset1:124
	s_waitcnt lgkmcnt(0)
	v_mfma_f32_16x16x32_bf16 v[84:87], v[88:91], v[28:31], v[84:87]
	v_mfma_f32_16x16x32_bf16 v[80:83], v[88:91], v[40:43], v[80:83]
	ds_read2_b64 v[88:91], v100 offset1:4
	s_waitcnt lgkmcnt(0)
	v_mfma_f32_16x16x32_bf16 v[92:95], v[88:91], v[16:19], 0
	v_mfma_f32_16x16x32_bf16 v[88:91], v[88:91], v[60:63], 0
	v_mfma_f32_16x16x32_bf16 v[92:95], v[96:99], v[12:15], v[92:95]
	v_mfma_f32_16x16x32_bf16 v[88:91], v[96:99], v[56:59], v[88:91]
	ds_read2_b64 v[96:99], v100 offset0:16 offset1:20
	s_waitcnt lgkmcnt(0)
	v_mfma_f32_16x16x32_bf16 v[92:95], v[96:99], v[8:11], v[92:95]
	v_mfma_f32_16x16x32_bf16 v[88:91], v[96:99], v[52:55], v[88:91]
	ds_read2_b64 v[96:99], v100 offset0:24 offset1:28
	s_waitcnt lgkmcnt(0)
	v_mfma_f32_16x16x32_bf16 v[92:95], v[96:99], v[4:7], v[92:95]
	v_mfma_f32_16x16x32_bf16 v[88:91], v[96:99], v[48:51], v[88:91]
	ds_read2_b64 v[96:99], v100 offset0:32 offset1:36
	s_waitcnt lgkmcnt(0)
	v_mfma_f32_16x16x32_bf16 v[92:95], v[96:99], v[0:3], v[92:95]
	v_mfma_f32_16x16x32_bf16 v[88:91], v[96:99], v[44:47], v[88:91]
	ds_read2_b64 v[96:99], v100 offset0:40 offset1:44
	s_waitcnt lgkmcnt(0)
	v_mfma_f32_16x16x32_bf16 v[92:95], v[96:99], v[20:23], v[92:95]
	v_mfma_f32_16x16x32_bf16 v[88:91], v[96:99], v[36:39], v[88:91]
	ds_read2_b64 v[96:99], v100 offset0:48 offset1:52
	s_waitcnt lgkmcnt(0)
	v_mfma_f32_16x16x32_bf16 v[92:95], v[96:99], v[24:27], v[92:95]
	v_mfma_f32_16x16x32_bf16 v[88:91], v[96:99], v[32:35], v[88:91]
	ds_read2_b64 v[96:99], v100 offset0:56 offset1:60
	s_waitcnt lgkmcnt(0)
	v_mfma_f32_16x16x32_bf16 v[92:95], v[96:99], v[28:31], v[92:95]
	v_mfma_f32_16x16x32_bf16 v[88:91], v[96:99], v[40:43], v[88:91]
	ds_read2_b64 v[96:99], v108 offset0:128 offset1:132
	s_waitcnt lgkmcnt(0)
	v_mfma_f32_16x16x32_bf16 v[100:103], v[96:99], v[16:19], 0
	v_mfma_f32_16x16x32_bf16 v[96:99], v[96:99], v[60:63], 0
	v_mfma_f32_16x16x32_bf16 v[100:103], v[104:107], v[12:15], v[100:103]
	v_mfma_f32_16x16x32_bf16 v[96:99], v[104:107], v[56:59], v[96:99]
	ds_read2_b64 v[104:107], v108 offset0:144 offset1:148
	s_waitcnt lgkmcnt(0)
	v_mfma_f32_16x16x32_bf16 v[100:103], v[104:107], v[8:11], v[100:103]
	v_mfma_f32_16x16x32_bf16 v[96:99], v[104:107], v[52:55], v[96:99]
	ds_read2_b64 v[104:107], v108 offset0:152 offset1:156
	s_waitcnt lgkmcnt(0)
	v_mfma_f32_16x16x32_bf16 v[100:103], v[104:107], v[4:7], v[100:103]
	v_mfma_f32_16x16x32_bf16 v[96:99], v[104:107], v[48:51], v[96:99]
	ds_read2_b64 v[104:107], v108 offset0:160 offset1:164
	s_waitcnt lgkmcnt(0)
	v_mfma_f32_16x16x32_bf16 v[100:103], v[104:107], v[0:3], v[100:103]
	v_mfma_f32_16x16x32_bf16 v[96:99], v[104:107], v[44:47], v[96:99]
	ds_read2_b64 v[104:107], v108 offset0:168 offset1:172
	s_waitcnt lgkmcnt(0)
	v_mfma_f32_16x16x32_bf16 v[100:103], v[104:107], v[20:23], v[100:103]
	v_mfma_f32_16x16x32_bf16 v[96:99], v[104:107], v[36:39], v[96:99]
	ds_read2_b64 v[104:107], v108 offset0:176 offset1:180
	s_waitcnt lgkmcnt(0)
	v_mfma_f32_16x16x32_bf16 v[100:103], v[104:107], v[24:27], v[100:103]
	v_mfma_f32_16x16x32_bf16 v[96:99], v[104:107], v[32:35], v[96:99]
	ds_read2_b64 v[104:107], v108 offset0:184 offset1:188
	s_waitcnt lgkmcnt(0)
	v_mfma_f32_16x16x32_bf16 v[100:103], v[104:107], v[28:31], v[100:103]
	v_mfma_f32_16x16x32_bf16 v[96:99], v[104:107], v[40:43], v[96:99]
	ds_read2_b64 v[104:107], v116 offset0:160 offset1:164
	s_waitcnt lgkmcnt(0)
	v_mfma_f32_16x16x32_bf16 v[108:111], v[104:107], v[16:19], 0
	v_mfma_f32_16x16x32_bf16 v[104:107], v[104:107], v[60:63], 0
	v_mfma_f32_16x16x32_bf16 v[108:111], v[112:115], v[12:15], v[108:111]
	v_mfma_f32_16x16x32_bf16 v[104:107], v[112:115], v[56:59], v[104:107]
	ds_read2_b64 v[112:115], v116 offset0:176 offset1:180
	s_waitcnt lgkmcnt(0)
	v_mfma_f32_16x16x32_bf16 v[108:111], v[112:115], v[8:11], v[108:111]
	v_mfma_f32_16x16x32_bf16 v[104:107], v[112:115], v[52:55], v[104:107]
	ds_read2_b64 v[112:115], v116 offset0:184 offset1:188
	s_waitcnt lgkmcnt(0)
	v_mfma_f32_16x16x32_bf16 v[108:111], v[112:115], v[4:7], v[108:111]
	v_mfma_f32_16x16x32_bf16 v[104:107], v[112:115], v[48:51], v[104:107]
	ds_read2_b64 v[112:115], v116 offset0:192 offset1:196
	s_waitcnt lgkmcnt(0)
	v_mfma_f32_16x16x32_bf16 v[108:111], v[112:115], v[0:3], v[108:111]
	v_mfma_f32_16x16x32_bf16 v[104:107], v[112:115], v[44:47], v[104:107]
	ds_read2_b64 v[112:115], v116 offset0:200 offset1:204
	s_waitcnt lgkmcnt(0)
	v_mfma_f32_16x16x32_bf16 v[108:111], v[112:115], v[20:23], v[108:111]
	v_mfma_f32_16x16x32_bf16 v[104:107], v[112:115], v[36:39], v[104:107]
	ds_read2_b64 v[112:115], v116 offset0:208 offset1:212
	s_waitcnt lgkmcnt(0)
	v_mfma_f32_16x16x32_bf16 v[108:111], v[112:115], v[24:27], v[108:111]
	v_mfma_f32_16x16x32_bf16 v[104:107], v[112:115], v[32:35], v[104:107]
	ds_read2_b64 v[112:115], v116 offset0:216 offset1:220
	s_waitcnt lgkmcnt(0)
	v_mfma_f32_16x16x32_bf16 v[108:111], v[112:115], v[28:31], v[108:111]
	v_mfma_f32_16x16x32_bf16 v[104:107], v[112:115], v[40:43], v[104:107]
	ds_read2_b64 v[112:115], v124 offset0:192 offset1:196
	s_waitcnt lgkmcnt(0)
	v_mfma_f32_16x16x32_bf16 v[116:119], v[112:115], v[16:19], 0
	v_mfma_f32_16x16x32_bf16 v[112:115], v[112:115], v[60:63], 0
	v_mfma_f32_16x16x32_bf16 v[116:119], v[120:123], v[12:15], v[116:119]
	v_mfma_f32_16x16x32_bf16 v[112:115], v[120:123], v[56:59], v[112:115]
	ds_read2_b64 v[120:123], v124 offset0:208 offset1:212
	s_waitcnt lgkmcnt(0)
	v_mfma_f32_16x16x32_bf16 v[116:119], v[120:123], v[8:11], v[116:119]
	v_mfma_f32_16x16x32_bf16 v[112:115], v[120:123], v[52:55], v[112:115]
	ds_read2_b64 v[120:123], v124 offset0:216 offset1:220
	s_waitcnt lgkmcnt(0)
	v_mfma_f32_16x16x32_bf16 v[116:119], v[120:123], v[4:7], v[116:119]
	v_mfma_f32_16x16x32_bf16 v[112:115], v[120:123], v[48:51], v[112:115]
	ds_read2_b64 v[120:123], v124 offset0:224 offset1:228
	s_waitcnt lgkmcnt(0)
	v_mfma_f32_16x16x32_bf16 v[116:119], v[120:123], v[0:3], v[116:119]
	v_mfma_f32_16x16x32_bf16 v[112:115], v[120:123], v[44:47], v[112:115]
	ds_read2_b64 v[120:123], v124 offset0:232 offset1:236
	s_waitcnt lgkmcnt(0)
	v_mfma_f32_16x16x32_bf16 v[116:119], v[120:123], v[20:23], v[116:119]
	v_mfma_f32_16x16x32_bf16 v[112:115], v[120:123], v[36:39], v[112:115]
	ds_read2_b64 v[120:123], v124 offset0:240 offset1:244
	s_waitcnt lgkmcnt(0)
	v_mfma_f32_16x16x32_bf16 v[116:119], v[120:123], v[24:27], v[116:119]
	v_mfma_f32_16x16x32_bf16 v[112:115], v[120:123], v[32:35], v[112:115]
	ds_read2_b64 v[120:123], v124 offset0:248 offset1:252
	s_waitcnt lgkmcnt(0)
	v_mfma_f32_16x16x32_bf16 v[116:119], v[120:123], v[28:31], v[116:119]
	v_mfma_f32_16x16x32_bf16 v[112:115], v[120:123], v[40:43], v[112:115]
	ds_read2_b64 v[120:123], v132 offset1:4
	s_waitcnt lgkmcnt(0)
	v_mfma_f32_16x16x32_bf16 v[124:127], v[120:123], v[16:19], 0
	v_mfma_f32_16x16x32_bf16 v[120:123], v[120:123], v[60:63], 0
	v_mfma_f32_16x16x32_bf16 v[124:127], v[128:131], v[12:15], v[124:127]
	v_mfma_f32_16x16x32_bf16 v[120:123], v[128:131], v[56:59], v[120:123]
	ds_read2_b64 v[128:131], v132 offset0:16 offset1:20
	s_waitcnt lgkmcnt(0)
	v_mfma_f32_16x16x32_bf16 v[124:127], v[128:131], v[8:11], v[124:127]
	v_mfma_f32_16x16x32_bf16 v[120:123], v[128:131], v[52:55], v[120:123]
	ds_read2_b64 v[128:131], v132 offset0:24 offset1:28
	s_waitcnt lgkmcnt(0)
	v_mfma_f32_16x16x32_bf16 v[124:127], v[128:131], v[4:7], v[124:127]
	v_mfma_f32_16x16x32_bf16 v[120:123], v[128:131], v[48:51], v[120:123]
	ds_read2_b64 v[128:131], v132 offset0:32 offset1:36
	s_waitcnt lgkmcnt(0)
	v_mfma_f32_16x16x32_bf16 v[124:127], v[128:131], v[0:3], v[124:127]
	v_mfma_f32_16x16x32_bf16 v[120:123], v[128:131], v[44:47], v[120:123]
	ds_read2_b64 v[128:131], v132 offset0:40 offset1:44
	s_waitcnt lgkmcnt(0)
	v_mfma_f32_16x16x32_bf16 v[124:127], v[128:131], v[20:23], v[124:127]
	v_mfma_f32_16x16x32_bf16 v[120:123], v[128:131], v[36:39], v[120:123]
	ds_read2_b64 v[128:131], v132 offset0:48 offset1:52
	s_waitcnt lgkmcnt(0)
	v_mfma_f32_16x16x32_bf16 v[124:127], v[128:131], v[24:27], v[124:127]
	v_mfma_f32_16x16x32_bf16 v[120:123], v[128:131], v[32:35], v[120:123]
	ds_read2_b64 v[128:131], v132 offset0:56 offset1:60
	s_waitcnt lgkmcnt(0)
	v_mfma_f32_16x16x32_bf16 v[124:127], v[128:131], v[28:31], v[124:127]
	v_mfma_f32_16x16x32_bf16 v[120:123], v[128:131], v[40:43], v[120:123]
	ds_read2_b64 v[128:131], v140 offset1:4
	s_waitcnt lgkmcnt(0)
	v_mfma_f32_16x16x32_bf16 v[132:135], v[128:131], v[16:19], 0
	v_mfma_f32_16x16x32_bf16 v[128:131], v[128:131], v[60:63], 0
	v_mfma_f32_16x16x32_bf16 v[132:135], v[136:139], v[12:15], v[132:135]
	v_mfma_f32_16x16x32_bf16 v[128:131], v[136:139], v[56:59], v[128:131]
	ds_read2_b64 v[136:139], v140 offset0:16 offset1:20
	s_waitcnt lgkmcnt(0)
	v_mfma_f32_16x16x32_bf16 v[132:135], v[136:139], v[8:11], v[132:135]
	v_mfma_f32_16x16x32_bf16 v[128:131], v[136:139], v[52:55], v[128:131]
	ds_read2_b64 v[136:139], v140 offset0:24 offset1:28
	s_waitcnt lgkmcnt(0)
	v_mfma_f32_16x16x32_bf16 v[132:135], v[136:139], v[4:7], v[132:135]
	v_mfma_f32_16x16x32_bf16 v[128:131], v[136:139], v[48:51], v[128:131]
	ds_read2_b64 v[136:139], v140 offset0:32 offset1:36
	s_waitcnt lgkmcnt(0)
	v_mfma_f32_16x16x32_bf16 v[132:135], v[136:139], v[0:3], v[132:135]
	v_mfma_f32_16x16x32_bf16 v[128:131], v[136:139], v[44:47], v[128:131]
	ds_read2_b64 v[136:139], v140 offset0:40 offset1:44
	s_waitcnt lgkmcnt(0)
	v_mfma_f32_16x16x32_bf16 v[132:135], v[136:139], v[20:23], v[132:135]
	v_mfma_f32_16x16x32_bf16 v[128:131], v[136:139], v[36:39], v[128:131]
	ds_read2_b64 v[136:139], v140 offset0:48 offset1:52
	s_waitcnt lgkmcnt(0)
	v_mfma_f32_16x16x32_bf16 v[132:135], v[136:139], v[24:27], v[132:135]
	v_mfma_f32_16x16x32_bf16 v[128:131], v[136:139], v[32:35], v[128:131]
	ds_read2_b64 v[136:139], v140 offset0:56 offset1:60
	s_waitcnt lgkmcnt(0)
	v_mfma_f32_16x16x32_bf16 v[132:135], v[136:139], v[28:31], v[132:135]
	v_mfma_f32_16x16x32_bf16 v[128:131], v[136:139], v[40:43], v[128:131]
	ds_read2_b64 v[136:139], v148 offset1:4
	s_waitcnt lgkmcnt(0)
	v_mfma_f32_16x16x32_bf16 v[140:143], v[136:139], v[16:19], 0
	v_mfma_f32_16x16x32_bf16 v[136:139], v[136:139], v[60:63], 0
	v_mfma_f32_16x16x32_bf16 v[140:143], v[144:147], v[12:15], v[140:143]
	v_mfma_f32_16x16x32_bf16 v[136:139], v[144:147], v[56:59], v[136:139]
	ds_read2_b64 v[144:147], v148 offset0:16 offset1:20
	s_waitcnt lgkmcnt(0)
	v_mfma_f32_16x16x32_bf16 v[140:143], v[144:147], v[8:11], v[140:143]
	v_mfma_f32_16x16x32_bf16 v[136:139], v[144:147], v[52:55], v[136:139]
	ds_read2_b64 v[144:147], v148 offset0:24 offset1:28
	s_waitcnt lgkmcnt(0)
	v_mfma_f32_16x16x32_bf16 v[140:143], v[144:147], v[4:7], v[140:143]
	v_mfma_f32_16x16x32_bf16 v[136:139], v[144:147], v[48:51], v[136:139]
	ds_read2_b64 v[144:147], v148 offset0:32 offset1:36
	s_waitcnt lgkmcnt(0)
	v_mfma_f32_16x16x32_bf16 v[140:143], v[144:147], v[0:3], v[140:143]
	v_mfma_f32_16x16x32_bf16 v[136:139], v[144:147], v[44:47], v[136:139]
	ds_read2_b64 v[144:147], v148 offset0:40 offset1:44
	s_waitcnt lgkmcnt(0)
	v_mfma_f32_16x16x32_bf16 v[140:143], v[144:147], v[20:23], v[140:143]
	v_mfma_f32_16x16x32_bf16 v[136:139], v[144:147], v[36:39], v[136:139]
	ds_read2_b64 v[144:147], v148 offset0:48 offset1:52
	s_waitcnt lgkmcnt(0)
	v_mfma_f32_16x16x32_bf16 v[140:143], v[144:147], v[24:27], v[140:143]
	v_mfma_f32_16x16x32_bf16 v[136:139], v[144:147], v[32:35], v[136:139]
	ds_read2_b64 v[144:147], v148 offset0:56 offset1:60
	s_waitcnt lgkmcnt(0)
	v_mfma_f32_16x16x32_bf16 v[140:143], v[144:147], v[28:31], v[140:143]
	v_mfma_f32_16x16x32_bf16 v[136:139], v[144:147], v[40:43], v[136:139]
	ds_read2_b64 v[144:147], v160 offset1:4
	s_waitcnt lgkmcnt(0)
	v_mfma_f32_16x16x32_bf16 v[148:151], v[144:147], v[16:19], 0
	v_mfma_f32_16x16x32_bf16 v[144:147], v[144:147], v[60:63], 0
	v_mfma_f32_16x16x32_bf16 v[148:151], v[156:159], v[12:15], v[148:151]
	v_mfma_f32_16x16x32_bf16 v[144:147], v[156:159], v[56:59], v[144:147]
	ds_read2_b64 v[156:159], v160 offset0:16 offset1:20
	s_waitcnt lgkmcnt(0)
	v_mfma_f32_16x16x32_bf16 v[148:151], v[156:159], v[8:11], v[148:151]
	v_mfma_f32_16x16x32_bf16 v[144:147], v[156:159], v[52:55], v[144:147]
	ds_read2_b64 v[156:159], v160 offset0:24 offset1:28
	s_waitcnt lgkmcnt(0)
	v_mfma_f32_16x16x32_bf16 v[148:151], v[156:159], v[4:7], v[148:151]
	v_mfma_f32_16x16x32_bf16 v[144:147], v[156:159], v[48:51], v[144:147]
	ds_read2_b64 v[156:159], v160 offset0:32 offset1:36
	s_waitcnt lgkmcnt(0)
	v_mfma_f32_16x16x32_bf16 v[148:151], v[156:159], v[0:3], v[148:151]
	v_mfma_f32_16x16x32_bf16 v[144:147], v[156:159], v[44:47], v[144:147]
	ds_read2_b64 v[156:159], v160 offset0:40 offset1:44
	s_waitcnt lgkmcnt(0)
	v_mfma_f32_16x16x32_bf16 v[148:151], v[156:159], v[20:23], v[148:151]
	v_mfma_f32_16x16x32_bf16 v[144:147], v[156:159], v[36:39], v[144:147]
	ds_read2_b64 v[156:159], v160 offset0:48 offset1:52
	s_waitcnt lgkmcnt(0)
	v_mfma_f32_16x16x32_bf16 v[148:151], v[156:159], v[24:27], v[148:151]
	v_mfma_f32_16x16x32_bf16 v[144:147], v[156:159], v[32:35], v[144:147]
	ds_read2_b64 v[156:159], v160 offset0:56 offset1:60
	s_waitcnt lgkmcnt(0)
	v_mfma_f32_16x16x32_bf16 v[148:151], v[156:159], v[28:31], v[148:151]
	v_mfma_f32_16x16x32_bf16 v[144:147], v[156:159], v[40:43], v[144:147]
	ds_read2_b64 v[156:159], v172 offset1:4
	s_waitcnt lgkmcnt(0)
	v_mfma_f32_16x16x32_bf16 v[160:163], v[156:159], v[16:19], 0
	v_mfma_f32_16x16x32_bf16 v[156:159], v[156:159], v[60:63], 0
	v_mfma_f32_16x16x32_bf16 v[160:163], v[164:167], v[12:15], v[160:163]
	v_mfma_f32_16x16x32_bf16 v[156:159], v[164:167], v[56:59], v[156:159]
	ds_read2_b64 v[164:167], v172 offset0:16 offset1:20
	s_waitcnt lgkmcnt(0)
	v_mfma_f32_16x16x32_bf16 v[160:163], v[164:167], v[8:11], v[160:163]
	v_mfma_f32_16x16x32_bf16 v[156:159], v[164:167], v[52:55], v[156:159]
	ds_read2_b64 v[164:167], v172 offset0:24 offset1:28
	s_waitcnt lgkmcnt(0)
	v_mfma_f32_16x16x32_bf16 v[160:163], v[164:167], v[4:7], v[160:163]
	v_mfma_f32_16x16x32_bf16 v[156:159], v[164:167], v[48:51], v[156:159]
	ds_read2_b64 v[164:167], v172 offset0:32 offset1:36
	s_waitcnt lgkmcnt(0)
	v_mfma_f32_16x16x32_bf16 v[160:163], v[164:167], v[0:3], v[160:163]
	v_mfma_f32_16x16x32_bf16 v[156:159], v[164:167], v[44:47], v[156:159]
	ds_read2_b64 v[164:167], v172 offset0:40 offset1:44
	s_waitcnt lgkmcnt(0)
	v_mfma_f32_16x16x32_bf16 v[160:163], v[164:167], v[20:23], v[160:163]
	v_mfma_f32_16x16x32_bf16 v[156:159], v[164:167], v[36:39], v[156:159]
	ds_read2_b64 v[164:167], v172 offset0:48 offset1:52
	ds_read2_b64 v[172:175], v172 offset0:56 offset1:60
	s_waitcnt lgkmcnt(1)
	v_mfma_f32_16x16x32_bf16 v[168:171], v[164:167], v[24:27], v[160:163]
	s_nop 2
	v_add_u32_e32 v163, v200, v207
	ds_read2_b64 v[176:179], v163 offset1:4
	v_add_f32_e32 v160, v152, v153
	v_add_f32_e32 v161, v154, v155
	v_mfma_f32_16x16x32_bf16 v[152:155], v[164:167], v[32:35], v[156:159]
	v_rcp_f32_e32 v160, v160
	v_rcp_f32_e32 v162, v161
	v_lshl_add_u64 v[164:165], v[194:195], 1, s[62:63]
	s_waitcnt lgkmcnt(1)
	v_mfma_f32_16x16x32_bf16 v[156:159], v[172:175], v[28:31], v[168:171]
	v_lshl_add_u64 v[164:165], v[164:165], 0, s[0:1]
	v_pk_mul_f32 v[68:69], v[160:161], v[68:69] op_sel_hi:[0,1]
	v_pk_mul_f32 v[70:71], v[160:161], v[70:71] op_sel_hi:[0,1]
	ds_read2_b64 v[166:169], v163 offset0:8 offset1:12
	v_mfma_f32_16x16x32_bf16 v[152:155], v[172:175], v[40:43], v[152:155]
	v_lshl_add_u64 v[164:165], v[164:165], 0, v[188:189]
	v_cvt_pk_bf16_f32 v174, v68, v69
	v_cvt_pk_bf16_f32 v175, v70, v71
	s_waitcnt lgkmcnt(1)
	v_mfma_f32_16x16x32_bf16 v[170:173], v[176:179], v[16:19], 0
	global_store_dwordx2 v[164:165], v[174:175], off
	v_pk_mul_f32 v[174:175], v[162:163], v[64:65] op_sel_hi:[0,1]
	v_pk_mul_f32 v[76:77], v[160:161], v[76:77] op_sel_hi:[0,1]
	v_mfma_f32_16x16x32_bf16 v[68:71], v[176:179], v[60:63], 0
	v_mul_f32_e64 v176, v162, v66
	v_mul_f32_e64 v177, v162, v67
	v_cvt_pk_bf16_f32 v178, v174, v175
	v_cvt_pk_bf16_f32 v179, v176, v177
	s_waitcnt lgkmcnt(0)
	v_mfma_f32_16x16x32_bf16 v[64:67], v[166:169], v[12:15], v[170:173]
	ds_read2_b64 v[174:177], v163 offset0:24 offset1:28
	v_pk_mul_f32 v[78:79], v[160:161], v[78:79] op_sel_hi:[0,1]
	v_pk_mul_f32 v[72:73], v[162:163], v[72:73] op_sel_hi:[0,1]
	ds_read2_b64 v[170:173], v163 offset0:16 offset1:20
	v_mfma_f32_16x16x32_bf16 v[68:71], v[166:169], v[56:59], v[68:71]
	v_cvt_pk_bf16_f32 v168, v76, v77
	v_cvt_pk_bf16_f32 v169, v78, v79
	ds_read2_b64 v[76:79], v163 offset0:32 offset1:36
	s_waitcnt lgkmcnt(1)
	v_mfma_f32_16x16x32_bf16 v[64:67], v[170:173], v[8:11], v[64:67]
	v_mul_f32_e64 v74, v162, v74
	v_mul_f32_e64 v75, v162, v75
	global_store_dwordx2 v[164:165], v[168:169], off offset:32
	v_cvt_pk_bf16_f32 v168, v72, v73
	v_mfma_f32_16x16x32_bf16 v[68:71], v[170:173], v[52:55], v[68:71]
	v_cvt_pk_bf16_f32 v169, v74, v75
	ds_read2_b64 v[72:75], v163 offset0:40 offset1:44
	v_add_co_u32_e32 v166, vcc, s8, v164
	v_mfma_f32_16x16x32_bf16 v[64:67], v[174:177], v[4:7], v[64:67]
	v_mul_f32_e64 v80, v162, v80
	v_mul_f32_e64 v81, v162, v81
	v_pk_mul_f32 v[82:83], v[162:163], v[82:83] op_sel_hi:[0,1]
	v_addc_co_u32_e32 v167, vcc, 0, v165, vcc
	v_mfma_f32_16x16x32_bf16 v[68:71], v[174:177], v[48:51], v[68:71]
	v_cvt_pk_bf16_f32 v80, v80, v81
	v_cvt_pk_bf16_f32 v81, v82, v83
	v_pk_mul_f32 v[84:85], v[160:161], v[84:85] op_sel_hi:[0,1]
	s_waitcnt lgkmcnt(1)
	v_mfma_f32_16x16x32_bf16 v[64:67], v[76:79], v[0:3], v[64:67]
	v_mul_f32_e64 v86, v160, v86
	v_mul_f32_e64 v87, v160, v87
	global_store_dwordx2 v[166:167], v[80:81], off offset:64
	v_pk_mul_f32 v[80:81], v[160:161], v[92:93] op_sel_hi:[0,1]
	v_mfma_f32_16x16x32_bf16 v[68:71], v[76:79], v[44:47], v[68:71]
	ds_read2_b64 v[76:79], v163 offset0:48 offset1:52
	v_add_u32_e32 v92, v200, v208
	v_cvt_pk_bf16_f32 v84, v84, v85
	s_waitcnt lgkmcnt(1)
	v_mfma_f32_16x16x32_bf16 v[64:67], v[72:75], v[20:23], v[64:67]
	v_cvt_pk_bf16_f32 v85, v86, v87
	v_cvt_pk_bf16_f32 v86, v80, v81
	ds_read2_b64 v[80:83], v92 offset1:4
	v_mfma_f32_16x16x32_bf16 v[68:71], v[72:75], v[36:39], v[68:71]
	ds_read2_b64 v[72:75], v163 offset0:56 offset1:60
	global_store_dwordx2 v[164:165], v[84:85], off offset:64
	v_pk_mul_f32 v[84:85], v[160:161], v[94:95] op_sel_hi:[0,1]
	s_waitcnt lgkmcnt(2)
	v_mfma_f32_16x16x32_bf16 v[64:67], v[76:79], v[24:27], v[64:67]
	v_cvt_pk_bf16_f32 v87, v84, v85
	global_store_dwordx2 v[164:165], v[86:87], off offset:96
	v_pk_mul_f32 v[84:85], v[162:163], v[88:89] op_sel_hi:[0,1]
	v_mfma_f32_16x16x32_bf16 v[76:79], v[76:79], v[32:35], v[68:71]
	v_mul_f32_e64 v86, v162, v90
	v_mul_f32_e64 v87, v162, v91
	v_cvt_pk_bf16_f32 v84, v84, v85
	v_cvt_pk_bf16_f32 v85, v86, v87
	s_waitcnt lgkmcnt(0)
	v_mfma_f32_16x16x32_bf16 v[68:71], v[72:75], v[28:31], v[64:67]
	global_store_dwordx2 v[166:167], v[84:85], off offset:96
	v_pk_mul_f32 v[84:85], v[160:161], v[100:101] op_sel_hi:[0,1]
	v_cvt_pk_bf16_f32 v90, v84, v85
	v_mfma_f32_16x16x32_bf16 v[64:67], v[72:75], v[40:43], v[76:79]
	ds_read2_b64 v[72:75], v92 offset0:8 offset1:12
	ds_read2_b64 v[84:87], v92 offset0:16 offset1:20
	v_pk_mul_f32 v[88:89], v[160:161], v[102:103] op_sel_hi:[0,1]
	v_mfma_f32_16x16x32_bf16 v[76:79], v[80:83], v[16:19], 0
	v_cvt_pk_bf16_f32 v91, v88, v89
	global_store_dwordx2 v[164:165], v[90:91], off offset:128
	v_pk_mul_f32 v[88:89], v[162:163], v[96:97] op_sel_hi:[0,1]
	v_mfma_f32_16x16x32_bf16 v[80:83], v[80:83], v[60:63], 0
	v_mul_f32_e64 v90, v162, v98
	v_mul_f32_e64 v91, v162, v99
	v_cvt_pk_bf16_f32 v88, v88, v89
	v_cvt_pk_bf16_f32 v89, v90, v91
	s_waitcnt lgkmcnt(1)
	v_mfma_f32_16x16x32_bf16 v[76:79], v[72:75], v[12:15], v[76:79]
	global_store_dwordx2 v[166:167], v[88:89], off offset:128
	v_pk_mul_f32 v[88:89], v[160:161], v[108:109] op_sel_hi:[0,1]
	v_pk_mul_f32 v[90:91], v[160:161], v[110:111] op_sel_hi:[0,1]
	v_mfma_f32_16x16x32_bf16 v[72:75], v[72:75], v[56:59], v[80:83]
	v_add_u32_e32 v100, v200, v209
	v_cvt_pk_bf16_f32 v88, v88, v89
	v_cvt_pk_bf16_f32 v89, v90, v91
	ds_read2_b64 v[80:83], v92 offset0:24 offset1:28
	s_waitcnt lgkmcnt(1)
	v_mfma_f32_16x16x32_bf16 v[76:79], v[84:87], v[8:11], v[76:79]
	global_store_dwordx2 v[164:165], v[88:89], off offset:160
	v_pk_mul_f32 v[88:89], v[162:163], v[104:105] op_sel_hi:[0,1]
	v_pk_mul_f32 v[90:91], v[162:163], v[106:107] op_sel_hi:[0,1]
	v_mfma_f32_16x16x32_bf16 v[72:75], v[84:87], v[52:55], v[72:75]
	ds_read2_b64 v[84:87], v92 offset0:32 offset1:36
	v_cvt_pk_bf16_f32 v88, v88, v89
	v_cvt_pk_bf16_f32 v89, v90, v91
	s_waitcnt lgkmcnt(1)
	v_mfma_f32_16x16x32_bf16 v[76:79], v[80:83], v[4:7], v[76:79]
	global_store_dwordx2 v[166:167], v[88:89], off offset:160
	v_pk_mul_f32 v[88:89], v[160:161], v[116:117] op_sel_hi:[0,1]
	v_pk_mul_f32 v[90:91], v[160:161], v[118:119] op_sel_hi:[0,1]
	v_mfma_f32_16x16x32_bf16 v[72:75], v[80:83], v[48:51], v[72:75]
	ds_read2_b64 v[80:83], v92 offset0:40 offset1:44
	v_cvt_pk_bf16_f32 v88, v88, v89
	v_cvt_pk_bf16_f32 v89, v90, v91
	s_waitcnt lgkmcnt(1)
	v_mfma_f32_16x16x32_bf16 v[76:79], v[84:87], v[0:3], v[76:79]
	global_store_dwordx2 v[164:165], v[88:89], off offset:192
	v_pk_mul_f32 v[88:89], v[162:163], v[112:113] op_sel_hi:[0,1]
	v_pk_mul_f32 v[90:91], v[162:163], v[114:115] op_sel_hi:[0,1]
	v_mfma_f32_16x16x32_bf16 v[72:75], v[84:87], v[44:47], v[72:75]
	ds_read2_b64 v[84:87], v92 offset0:48 offset1:52
	v_cvt_pk_bf16_f32 v88, v88, v89
	v_cvt_pk_bf16_f32 v89, v90, v91
	s_waitcnt lgkmcnt(1)
	v_mfma_f32_16x16x32_bf16 v[76:79], v[80:83], v[20:23], v[76:79]
	global_store_dwordx2 v[166:167], v[88:89], off offset:192
	v_pk_mul_f32 v[88:89], v[160:161], v[124:125] op_sel_hi:[0,1]
	v_pk_mul_f32 v[90:91], v[160:161], v[126:127] op_sel_hi:[0,1]
	v_mfma_f32_16x16x32_bf16 v[72:75], v[80:83], v[36:39], v[72:75]
	ds_read2_b64 v[80:83], v92 offset0:56 offset1:60
	v_pk_mul_f32 v[92:93], v[162:163], v[120:121] op_sel_hi:[0,1]
	v_pk_mul_f32 v[94:95], v[162:163], v[122:123] op_sel_hi:[0,1]
	s_waitcnt lgkmcnt(1)
	v_mfma_f32_16x16x32_bf16 v[76:79], v[84:87], v[24:27], v[76:79]
	v_cvt_pk_bf16_f32 v88, v88, v89
	v_cvt_pk_bf16_f32 v89, v90, v91
	v_cvt_pk_bf16_f32 v92, v92, v93
	v_mfma_f32_16x16x32_bf16 v[72:75], v[84:87], v[32:35], v[72:75]
	ds_read2_b64 v[84:87], v100 offset1:4
	v_cvt_pk_bf16_f32 v93, v94, v95
	global_store_dwordx2 v[164:165], v[88:89], off offset:224
	s_waitcnt lgkmcnt(1)
	v_mfma_f32_16x16x32_bf16 v[76:79], v[80:83], v[28:31], v[76:79]
	global_store_dwordx2 v[166:167], v[92:93], off offset:224
	ds_read2_b64 v[92:95], v100 offset0:16 offset1:20
	v_pk_mul_f32 v[68:69], v[160:161], v[68:69] op_sel_hi:[0,1]
	v_mfma_f32_16x16x32_bf16 v[72:75], v[80:83], v[40:43], v[72:75]
	ds_read2_b64 v[80:83], v100 offset0:8 offset1:12
	v_cvt_pk_bf16_f32 v68, v68, v69
	v_pk_mul_f32 v[96:97], v[160:161], v[132:133] op_sel_hi:[0,1]
	s_waitcnt lgkmcnt(2)
	v_mfma_f32_16x16x32_bf16 v[88:91], v[84:87], v[16:19], 0
	v_mul_f32_e64 v98, v160, v134
	v_mul_f32_e64 v99, v160, v135
	v_cvt_pk_bf16_f32 v96, v96, v97
	v_cvt_pk_bf16_f32 v97, v98, v99
	v_mfma_f32_16x16x32_bf16 v[84:87], v[84:87], v[60:63], 0
	global_store_dwordx2 v[164:165], v[96:97], off offset:256
	v_pk_mul_f32 v[96:97], v[162:163], v[128:129] op_sel_hi:[0,1]
	v_pk_mul_f32 v[98:99], v[162:163], v[130:131] op_sel_hi:[0,1]
	s_waitcnt lgkmcnt(0)
	v_mfma_f32_16x16x32_bf16 v[88:91], v[80:83], v[12:15], v[88:91]
	v_cvt_pk_bf16_f32 v96, v96, v97
	v_cvt_pk_bf16_f32 v97, v98, v99
	global_store_dwordx2 v[166:167], v[96:97], off offset:256
	v_mfma_f32_16x16x32_bf16 v[80:83], v[80:83], v[56:59], v[84:87]
	v_mul_f32_e64 v96, v160, v140
	v_mul_f32_e64 v97, v160, v141
	v_pk_mul_f32 v[98:99], v[160:161], v[142:143] op_sel_hi:[0,1]
	v_cvt_pk_bf16_f32 v96, v96, v97
	ds_read2_b64 v[84:87], v100 offset0:24 offset1:28
	v_mfma_f32_16x16x32_bf16 v[88:91], v[92:95], v[8:11], v[88:91]
	v_cvt_pk_bf16_f32 v97, v98, v99
	global_store_dwordx2 v[164:165], v[96:97], off offset:288
	v_pk_mul_f32 v[96:97], v[162:163], v[136:137] op_sel_hi:[0,1]
	v_mfma_f32_16x16x32_bf16 v[80:83], v[92:95], v[52:55], v[80:83]
	ds_read2_b64 v[92:95], v100 offset0:32 offset1:36
	v_pk_mul_f32 v[98:99], v[162:163], v[138:139] op_sel_hi:[0,1]
	v_cvt_pk_bf16_f32 v96, v96, v97
	s_waitcnt lgkmcnt(1)
	v_mfma_f32_16x16x32_bf16 v[88:91], v[84:87], v[4:7], v[88:91]
	v_cvt_pk_bf16_f32 v97, v98, v99
	global_store_dwordx2 v[166:167], v[96:97], off offset:288
	v_pk_mul_f32 v[96:97], v[160:161], v[148:149] op_sel_hi:[0,1]
	v_mfma_f32_16x16x32_bf16 v[80:83], v[84:87], v[48:51], v[80:83]
	ds_read2_b64 v[84:87], v100 offset0:40 offset1:44
	v_pk_mul_f32 v[98:99], v[160:161], v[150:151] op_sel_hi:[0,1]
	v_cvt_pk_bf16_f32 v96, v96, v97
	s_waitcnt lgkmcnt(1)
	v_mfma_f32_16x16x32_bf16 v[88:91], v[92:95], v[0:3], v[88:91]
	v_cvt_pk_bf16_f32 v97, v98, v99
	global_store_dwordx2 v[164:165], v[96:97], off offset:320
	v_pk_mul_f32 v[96:97], v[162:163], v[144:145] op_sel_hi:[0,1]
	v_mfma_f32_16x16x32_bf16 v[80:83], v[92:95], v[44:47], v[80:83]
	ds_read2_b64 v[92:95], v100 offset0:48 offset1:52
	v_pk_mul_f32 v[98:99], v[162:163], v[146:147] op_sel_hi:[0,1]
	v_cvt_pk_bf16_f32 v96, v96, v97
	s_waitcnt lgkmcnt(1)
	v_mfma_f32_16x16x32_bf16 v[88:91], v[84:87], v[20:23], v[88:91]
	v_cvt_pk_bf16_f32 v97, v98, v99
	global_store_dwordx2 v[166:167], v[96:97], off offset:320
	v_pk_mul_f32 v[96:97], v[160:161], v[156:157] op_sel_hi:[0,1]
	v_mfma_f32_16x16x32_bf16 v[80:83], v[84:87], v[36:39], v[80:83]
	ds_read2_b64 v[84:87], v100 offset0:56 offset1:60
	v_add_u32_e32 v100, v200, v210
	v_pk_mul_f32 v[98:99], v[160:161], v[158:159] op_sel_hi:[0,1]
	s_waitcnt lgkmcnt(1)
	v_mfma_f32_16x16x32_bf16 v[88:91], v[92:95], v[24:27], v[88:91]
	v_cvt_pk_bf16_f32 v96, v96, v97
	v_cvt_pk_bf16_f32 v97, v98, v99
	global_store_dwordx2 v[164:165], v[96:97], off offset:352
	v_mfma_f32_16x16x32_bf16 v[80:83], v[92:95], v[32:35], v[80:83]
	ds_read2_b64 v[92:95], v100 offset1:4
	v_pk_mul_f32 v[96:97], v[162:163], v[152:153] op_sel_hi:[0,1]
	v_pk_mul_f32 v[98:99], v[162:163], v[154:155] op_sel_hi:[0,1]
	s_waitcnt lgkmcnt(1)
	v_mfma_f32_16x16x32_bf16 v[88:91], v[84:87], v[28:31], v[88:91]
	v_cvt_pk_bf16_f32 v96, v96, v97
	v_cvt_pk_bf16_f32 v97, v98, v99
	global_store_dwordx2 v[166:167], v[178:179], off
	v_mfma_f32_16x16x32_bf16 v[80:83], v[84:87], v[40:43], v[80:83]
	ds_read2_b64 v[84:87], v100 offset0:8 offset1:12
	global_store_dwordx2 v[166:167], v[168:169], off offset:32
	global_store_dwordx2 v[166:167], v[96:97], off offset:352
	s_waitcnt lgkmcnt(1)
	v_mfma_f32_16x16x32_bf16 v[16:19], v[92:95], v[16:19], 0
	v_mfma_f32_16x16x32_bf16 v[60:63], v[92:95], v[60:63], 0
	ds_read2_b64 v[92:95], v100 offset0:16 offset1:20
	s_waitcnt lgkmcnt(1)
	v_mfma_f32_16x16x32_bf16 v[12:15], v[84:87], v[12:15], v[16:19]
	s_nop 3
	v_mul_f32_e64 v16, v160, v70
	v_mul_f32_e64 v17, v160, v71
	v_cvt_pk_bf16_f32 v69, v16, v17
	v_mfma_f32_16x16x32_bf16 v[16:19], v[84:87], v[56:59], v[60:63]
	ds_read2_b64 v[56:59], v100 offset0:24 offset1:28
	global_store_dwordx2 v[164:165], v[68:69], off offset:384
	s_nop 0
	v_pk_mul_f32 v[60:61], v[162:163], v[64:65] op_sel_hi:[0,1]
	s_waitcnt lgkmcnt(1)
	v_mfma_f32_16x16x32_bf16 v[8:11], v[92:95], v[8:11], v[12:15]
	v_cvt_pk_bf16_f32 v60, v60, v61
	s_nop 1
	v_pk_mul_f32 v[12:13], v[162:163], v[66:67] op_sel_hi:[0,1]
	v_cvt_pk_bf16_f32 v61, v12, v13
	v_mfma_f32_16x16x32_bf16 v[12:15], v[92:95], v[52:55], v[16:19]
	v_mul_f32_e64 v52, v160, v76
	v_mul_f32_e64 v53, v160, v77
	v_cvt_pk_bf16_f32 v52, v52, v53
	global_store_dwordx2 v[166:167], v[60:61], off offset:384
	ds_read2_b64 v[16:19], v100 offset0:32 offset1:36
	s_waitcnt lgkmcnt(1)
	v_mfma_f32_16x16x32_bf16 v[4:7], v[56:59], v[4:7], v[8:11]
	s_nop 2
	v_mul_f32_e64 v8, v160, v78
	v_mul_f32_e64 v9, v160, v79
	v_cvt_pk_bf16_f32 v53, v8, v9
	v_mfma_f32_16x16x32_bf16 v[8:11], v[56:59], v[48:51], v[12:15]
	v_mul_f32_e64 v48, v162, v72
	v_mul_f32_e64 v49, v162, v73
	v_cvt_pk_bf16_f32 v48, v48, v49
	global_store_dwordx2 v[164:165], v[52:53], off offset:416
	ds_read2_b64 v[12:15], v100 offset0:40 offset1:44
	s_waitcnt lgkmcnt(1)
	v_mfma_f32_16x16x32_bf16 v[0:3], v[16:19], v[0:3], v[4:7]
	s_nop 2
	v_mul_f32_e64 v4, v162, v74
	v_mul_f32_e64 v5, v162, v75
	v_cvt_pk_bf16_f32 v49, v4, v5
	v_mfma_f32_16x16x32_bf16 v[4:7], v[16:19], v[44:47], v[8:11]
	v_mul_f32_e64 v16, v160, v88
	v_mul_f32_e64 v17, v160, v89
	global_store_dwordx2 v[166:167], v[48:49], off offset:416
	ds_read2_b64 v[8:11], v100 offset0:48 offset1:52
	s_waitcnt lgkmcnt(1)
	v_mfma_f32_16x16x32_bf16 v[0:3], v[12:15], v[20:23], v[0:3]
	v_cvt_pk_bf16_f32 v22, v16, v17
	ds_read2_b64 v[16:19], v100 offset0:56 offset1:60
	v_pk_mul_f32 v[20:21], v[160:161], v[90:91] op_sel_hi:[0,1]
	s_waitcnt lgkmcnt(1)
	v_mfma_f32_16x16x32_bf16 v[0:3], v[8:11], v[24:27], v[0:3]
	v_cvt_pk_bf16_f32 v23, v20, v21
	global_store_dwordx2 v[164:165], v[22:23], off offset:448
	v_mfma_f32_16x16x32_bf16 v[4:7], v[12:15], v[36:39], v[4:7]
	v_mul_f32_e64 v12, v162, v80
	v_mul_f32_e64 v13, v162, v81
	v_pk_mul_f32 v[14:15], v[162:163], v[82:83] op_sel_hi:[0,1]
	v_cvt_pk_bf16_f32 v12, v12, v13
	s_waitcnt lgkmcnt(0)
	v_mfma_f32_16x16x32_bf16 v[0:3], v[16:19], v[28:31], v[0:3]
	v_cvt_pk_bf16_f32 v13, v14, v15
	global_store_dwordx2 v[166:167], v[12:13], off offset:448
	s_nop 5
	v_pk_mul_f32 v[12:13], v[160:161], v[0:1] op_sel_hi:[0,1]
	v_pk_mul_f32 v[14:15], v[160:161], v[2:3] op_sel_hi:[0,1]
	v_mfma_f32_16x16x32_bf16 v[0:3], v[8:11], v[32:35], v[4:7]
	v_mfma_f32_16x16x32_bf16 v[0:3], v[16:19], v[40:43], v[0:3]
	s_nop 1
	v_cvt_pk_bf16_f32 v4, v12, v13
	v_cvt_pk_bf16_f32 v5, v14, v15
	global_store_dwordx2 v[164:165], v[4:5], off offset:480
	s_nop 2
	v_pk_mul_f32 v[0:1], v[162:163], v[0:1] op_sel_hi:[0,1]
	v_pk_mul_f32 v[2:3], v[162:163], v[2:3] op_sel_hi:[0,1]
	v_cvt_pk_bf16_f32 v0, v0, v1
	v_cvt_pk_bf16_f32 v1, v2, v3
	global_store_dwordx2 v[166:167], v[0:1], off offset:480
	s_barrier
	s_cbranch_scc0 .LBB0_501
